# rq tile staging ratio changed: rows 0-31 by LDS-DMA (4 per wave), rows 32-127 through registers in one batch of 12 loads
# baseline (speedup 1.0000x reference)
.LBB0_327:
	v_mov_b32_e32 v130, s67
	v_mov_b32_e32 v131, s66
	v_cndmask_b32_e32 v130, v130, v131, vcc
	v_lshl_add_u32 v168, v130, 7, v155
	v_mov_b32_e32 v153, v161
	v_mov_b32_e32 v192, v181
	v_mov_b32_e32 v190, v183
	v_mov_b32_e32 v191, v182
	v_mov_b32_e32 v166, v157
	v_mov_b32_e32 v130, v186
	v_mov_b32_e32 v131, v187
	v_ashrrev_i32_e32 v169, 31, v168
	v_readfirstlane_b32 s64, v130
	v_readfirstlane_b32 s65, v131
	v_lshlrev_b64 v[130:131], 11, v[168:169]
	v_mov_b32_e32 v167, v189
	s_barrier
	v_lshl_add_u64 v[244:245], s[64:65], 0, v[130:131]
	v_lshl_add_u64 v[244:245], v[244:245], 0, v[0:1]
	s_mov_b32 s6, 0xc640000
	s_mov_b32 s7, 0
	v_lshl_add_u64 v[244:245], v[244:245], 0, s[6:7]
	v_and_b32_e32 v247, 0xff, v189
	v_lshrrev_b32_e32 v248, 5, v247
	v_and_b32_e32 v247, 31, v247
	v_add_u32_e32 v249, 32, v248
	v_lshlrev_b32_e32 v249, 11, v249
	v_lshl_add_u32 v242, v247, 4, v249
	v_mov_b32_e32 v243, 0
	v_lshl_add_u64 v[242:243], v[244:245], 0, v[242:243]
	v_lshrrev_b32_e32 v249, 1, v248
	v_add_u32_e32 v249, 16, v249
	v_mul_u32_u24_e32 v249, 0x410, v249
	v_and_b32_e32 v248, 1, v248
	v_lshl_add_u32 v249, v248, 9, v249
	v_lshl_add_u32 v249, v247, 4, v249
	v_add_u32_e32 v246, v149, v249
	s_mov_b32 s6, 0x4000
	global_load_dwordx4 v[130:133], v[242:243], off
	v_lshl_add_u64 v[242:243], v[242:243], 0, s[6:7]
	global_load_dwordx4 v[134:137], v[242:243], off
	v_lshl_add_u64 v[242:243], v[242:243], 0, s[6:7]
	global_load_dwordx4 v[138:141], v[242:243], off
	v_lshl_add_u64 v[242:243], v[242:243], 0, s[6:7]
	global_load_dwordx4 v[142:145], v[242:243], off
	v_lshl_add_u64 v[242:243], v[242:243], 0, s[6:7]
	global_load_dwordx4 v[170:173], v[242:243], off
	v_lshl_add_u64 v[242:243], v[242:243], 0, s[6:7]
	global_load_dwordx4 v[194:197], v[242:243], off
	v_lshl_add_u64 v[242:243], v[242:243], 0, s[6:7]
	global_load_dwordx4 v[218:221], v[242:243], off
	v_lshl_add_u64 v[242:243], v[242:243], 0, s[6:7]
	global_load_dwordx4 v[222:225], v[242:243], off
	v_lshl_add_u64 v[242:243], v[242:243], 0, s[6:7]
	global_load_dwordx4 v[226:229], v[242:243], off
	v_lshl_add_u64 v[242:243], v[242:243], 0, s[6:7]
	global_load_dwordx4 v[230:233], v[242:243], off
	v_lshl_add_u64 v[242:243], v[242:243], 0, s[6:7]
	global_load_dwordx4 v[234:237], v[242:243], off
	v_lshl_add_u64 v[242:243], v[242:243], 0, s[6:7]
	global_load_dwordx4 v[238:241], v[242:243], off
	v_bfe_u32 v248, v189, 6, 2
	v_lshlrev_b32_e32 v248, 3, v248
	v_bfe_u32 v249, v189, 5, 1
	v_add_u32_e32 v248, v248, v249
	v_lshlrev_b32_e32 v248, 11, v248
	v_and_b32_e32 v249, 31, v189
	v_lshl_add_u32 v248, v249, 4, v248
	v_mov_b32_e32 v249, 0
	v_lshl_add_u64 v[244:245], v[244:245], 0, v[248:249]
	v_readfirstlane_b32 s6, v149
	v_readfirstlane_b32 s7, v189
	s_nop 3
	s_bfe_u32 s7, s7, 0x20006
	s_mul_i32 s7, s7, 0x1040
	s_add_u32 s6, s6, s7
	s_mov_b32 m0, s6
	s_mov_b32 s6, 0x1000
	s_mov_b32 s7, 0
	global_load_lds_dwordx4 v[244:245], off
	s_add_u32 m0, m0, 0x410
	v_lshl_add_u64 v[244:245], v[244:245], 0, s[6:7]
	global_load_lds_dwordx4 v[244:245], off
	s_add_u32 m0, m0, 0x410
	v_lshl_add_u64 v[244:245], v[244:245], 0, s[6:7]
	global_load_lds_dwordx4 v[244:245], off
	s_add_u32 m0, m0, 0x410
	v_lshl_add_u64 v[244:245], v[244:245], 0, s[6:7]
	global_load_lds_dwordx4 v[244:245], off
	s_waitcnt vmcnt(15)
	ds_write2_b64 v246, v[130:131], v[132:133] offset1:1
	s_waitcnt vmcnt(14)
	v_add_u32_e32 v247, 0x1040, v246
	ds_write2_b64 v247, v[134:135], v[136:137] offset1:1
	s_waitcnt vmcnt(13)
	v_add_u32_e32 v247, 0x2080, v246
	ds_write2_b64 v247, v[138:139], v[140:141] offset1:1
	s_waitcnt vmcnt(12)
	v_add_u32_e32 v247, 0x30c0, v246
	ds_write2_b64 v247, v[142:143], v[144:145] offset1:1
	s_waitcnt vmcnt(11)
	v_add_u32_e32 v247, 0x4100, v246
	ds_write2_b64 v247, v[170:171], v[172:173] offset1:1
	s_waitcnt vmcnt(10)
	v_add_u32_e32 v247, 0x5140, v246
	ds_write2_b64 v247, v[194:195], v[196:197] offset1:1
	s_waitcnt vmcnt(9)
	v_add_u32_e32 v247, 0x6180, v246
	ds_write2_b64 v247, v[218:219], v[220:221] offset1:1
	s_waitcnt vmcnt(8)
	v_add_u32_e32 v247, 0x71c0, v246
	ds_write2_b64 v247, v[222:223], v[224:225] offset1:1
	s_waitcnt vmcnt(7)
	v_add_u32_e32 v247, 0x8200, v246
	ds_write2_b64 v247, v[226:227], v[228:229] offset1:1
	s_waitcnt vmcnt(6)
	v_add_u32_e32 v247, 0x9240, v246
	ds_write2_b64 v247, v[230:231], v[232:233] offset1:1
	s_waitcnt vmcnt(5)
	v_add_u32_e32 v247, 0xa280, v246
	ds_write2_b64 v247, v[234:235], v[236:237] offset1:1
	s_waitcnt vmcnt(4)
	v_add_u32_e32 v247, 0xb2c0, v246
	ds_write2_b64 v247, v[238:239], v[240:241] offset1:1
	v_lshl_add_u64 v[210:211], s[64:65], 0, v[162:163]
	s_waitcnt vmcnt(0)
	s_waitcnt lgkmcnt(0)
	s_barrier
	v_ashrrev_i32_e32 v167, 31, v166
	v_lshl_add_u64 v[130:131], v[166:167], 1, v[210:211]
	s_mov_b64 s[6:7], 0x8640000
	v_lshl_add_u64 v[170:171], v[130:131], 0, s[6:7]
	v_add_u32_e32 v250, 0x4000, v178
	ds_read2_b64 v[194:197], v178 offset0:0 offset1:2
	ds_read2_b64 v[218:221], v250 offset0:32 offset1:34
	ds_read2_b64 v[222:225], v178 offset0:4 offset1:6
	ds_read2_b64 v[226:229], v250 offset0:36 offset1:38
	s_nop 0
	v_cvt_pk_bf16_f32 v230, v2, v3
	v_cvt_pk_bf16_f32 v231, v4, v5
	v_cvt_pk_bf16_f32 v232, v6, v7
	v_cvt_pk_bf16_f32 v233, v8, v9
	s_waitcnt lgkmcnt(2)
	s_nop 1
	v_mfma_f32_32x32x16_bf16 v[130:145], v[194:197], v[230:233], 0
	v_mfma_f32_32x32x16_bf16 v[234:249], v[218:221], v[230:233], 0
	ds_read2_b64 v[194:197], v178 offset0:8 offset1:10
	ds_read2_b64 v[218:221], v250 offset0:40 offset1:42
	s_nop 0
	v_cvt_pk_bf16_f32 v230, v10, v11
	v_cvt_pk_bf16_f32 v231, v12, v13
	v_cvt_pk_bf16_f32 v232, v14, v15
	v_cvt_pk_bf16_f32 v233, v16, v17
	s_waitcnt lgkmcnt(2)
	s_nop 1
	v_mfma_f32_32x32x16_bf16 v[130:145], v[222:225], v[230:233], v[130:145]
	v_mfma_f32_32x32x16_bf16 v[234:249], v[226:229], v[230:233], v[234:249]
	ds_read2_b64 v[222:225], v178 offset0:12 offset1:14
	ds_read2_b64 v[226:229], v250 offset0:44 offset1:46
	s_nop 0
	v_cvt_pk_bf16_f32 v230, v18, v19
	v_cvt_pk_bf16_f32 v231, v20, v21
	v_cvt_pk_bf16_f32 v232, v22, v23
	v_cvt_pk_bf16_f32 v233, v24, v25
	s_waitcnt lgkmcnt(2)
	s_nop 1
	v_mfma_f32_32x32x16_bf16 v[130:145], v[194:197], v[230:233], v[130:145]
	v_mfma_f32_32x32x16_bf16 v[234:249], v[218:221], v[230:233], v[234:249]
	ds_read2_b64 v[194:197], v178 offset0:16 offset1:18
	ds_read2_b64 v[218:221], v250 offset0:48 offset1:50
	s_nop 0
	v_cvt_pk_bf16_f32 v230, v26, v27
	v_cvt_pk_bf16_f32 v231, v28, v29
	v_cvt_pk_bf16_f32 v232, v30, v31
	v_cvt_pk_bf16_f32 v233, v32, v33
	s_waitcnt lgkmcnt(2)
	s_nop 1
	v_mfma_f32_32x32x16_bf16 v[130:145], v[222:225], v[230:233], v[130:145]
	v_mfma_f32_32x32x16_bf16 v[234:249], v[226:229], v[230:233], v[234:249]
	ds_read2_b64 v[222:225], v178 offset0:20 offset1:22
	ds_read2_b64 v[226:229], v250 offset0:52 offset1:54
	s_nop 0
	v_cvt_pk_bf16_f32 v230, v34, v35
	v_cvt_pk_bf16_f32 v231, v36, v37
	v_cvt_pk_bf16_f32 v232, v38, v39
	v_cvt_pk_bf16_f32 v233, v40, v41
	s_waitcnt lgkmcnt(2)
	s_nop 1
	v_mfma_f32_32x32x16_bf16 v[130:145], v[194:197], v[230:233], v[130:145]
	v_mfma_f32_32x32x16_bf16 v[234:249], v[218:221], v[230:233], v[234:249]
	ds_read2_b64 v[194:197], v178 offset0:24 offset1:26
	ds_read2_b64 v[218:221], v250 offset0:56 offset1:58
	s_nop 0
	v_cvt_pk_bf16_f32 v230, v42, v43
	v_cvt_pk_bf16_f32 v231, v44, v45
	v_cvt_pk_bf16_f32 v232, v46, v47
	v_cvt_pk_bf16_f32 v233, v48, v49
	s_waitcnt lgkmcnt(2)
	s_nop 1
	v_mfma_f32_32x32x16_bf16 v[130:145], v[222:225], v[230:233], v[130:145]
	v_mfma_f32_32x32x16_bf16 v[234:249], v[226:229], v[230:233], v[234:249]
	ds_read2_b64 v[222:225], v178 offset0:28 offset1:30
	ds_read2_b64 v[226:229], v250 offset0:60 offset1:62
	s_nop 0
	v_cvt_pk_bf16_f32 v230, v50, v51
	v_cvt_pk_bf16_f32 v231, v52, v53
	v_cvt_pk_bf16_f32 v232, v54, v55
	v_cvt_pk_bf16_f32 v233, v56, v57
	s_waitcnt lgkmcnt(2)
	s_nop 1
	v_mfma_f32_32x32x16_bf16 v[130:145], v[194:197], v[230:233], v[130:145]
	v_mfma_f32_32x32x16_bf16 v[234:249], v[218:221], v[230:233], v[234:249]
	ds_read2_b64 v[194:197], v178 offset0:32 offset1:34
	ds_read2_b64 v[218:221], v250 offset0:64 offset1:66
	s_nop 0
	v_cvt_pk_bf16_f32 v230, v58, v59
	v_cvt_pk_bf16_f32 v231, v60, v61
	v_cvt_pk_bf16_f32 v232, v62, v63
	v_cvt_pk_bf16_f32 v233, v64, v65
	s_waitcnt lgkmcnt(2)
	s_nop 1
	v_mfma_f32_32x32x16_bf16 v[130:145], v[222:225], v[230:233], v[130:145]
	v_mfma_f32_32x32x16_bf16 v[234:249], v[226:229], v[230:233], v[234:249]
	ds_read2_b64 v[222:225], v178 offset0:36 offset1:38
	ds_read2_b64 v[226:229], v250 offset0:68 offset1:70
	s_nop 0
	v_cvt_pk_bf16_f32 v230, v66, v67
	v_cvt_pk_bf16_f32 v231, v68, v69
	v_cvt_pk_bf16_f32 v232, v70, v71
	v_cvt_pk_bf16_f32 v233, v72, v73
	s_waitcnt lgkmcnt(2)
	s_nop 1
	v_mfma_f32_32x32x16_bf16 v[130:145], v[194:197], v[230:233], v[130:145]
	v_mfma_f32_32x32x16_bf16 v[234:249], v[218:221], v[230:233], v[234:249]
	ds_read2_b64 v[194:197], v178 offset0:40 offset1:42
	ds_read2_b64 v[218:221], v250 offset0:72 offset1:74
	s_nop 0
	v_cvt_pk_bf16_f32 v230, v74, v75
	v_cvt_pk_bf16_f32 v231, v76, v77
	v_cvt_pk_bf16_f32 v232, v78, v79
	v_cvt_pk_bf16_f32 v233, v80, v81
	s_waitcnt lgkmcnt(2)
	s_nop 1
	v_mfma_f32_32x32x16_bf16 v[130:145], v[222:225], v[230:233], v[130:145]
	v_mfma_f32_32x32x16_bf16 v[234:249], v[226:229], v[230:233], v[234:249]
	ds_read2_b64 v[222:225], v178 offset0:44 offset1:46
	ds_read2_b64 v[226:229], v250 offset0:76 offset1:78
	s_nop 0
	v_cvt_pk_bf16_f32 v230, v82, v83
	v_cvt_pk_bf16_f32 v231, v84, v85
	v_cvt_pk_bf16_f32 v232, v86, v87
	v_cvt_pk_bf16_f32 v233, v88, v89
	s_waitcnt lgkmcnt(2)
	s_nop 1
	v_mfma_f32_32x32x16_bf16 v[130:145], v[194:197], v[230:233], v[130:145]
	v_mfma_f32_32x32x16_bf16 v[234:249], v[218:221], v[230:233], v[234:249]
	ds_read2_b64 v[194:197], v178 offset0:48 offset1:50
	ds_read2_b64 v[218:221], v250 offset0:80 offset1:82
	s_nop 0
	v_cvt_pk_bf16_f32 v230, v90, v91
	v_cvt_pk_bf16_f32 v231, v92, v93
	v_cvt_pk_bf16_f32 v232, v94, v95
	v_cvt_pk_bf16_f32 v233, v96, v97
	s_waitcnt lgkmcnt(2)
	s_nop 1
	v_mfma_f32_32x32x16_bf16 v[130:145], v[222:225], v[230:233], v[130:145]
	v_mfma_f32_32x32x16_bf16 v[234:249], v[226:229], v[230:233], v[234:249]
	ds_read2_b64 v[222:225], v178 offset0:52 offset1:54
	ds_read2_b64 v[226:229], v250 offset0:84 offset1:86
	s_nop 0
	v_cvt_pk_bf16_f32 v230, v98, v99
	v_cvt_pk_bf16_f32 v231, v100, v101
	v_cvt_pk_bf16_f32 v232, v102, v103
	v_cvt_pk_bf16_f32 v233, v104, v105
	s_waitcnt lgkmcnt(2)
	s_nop 1
	v_mfma_f32_32x32x16_bf16 v[130:145], v[194:197], v[230:233], v[130:145]
	v_mfma_f32_32x32x16_bf16 v[234:249], v[218:221], v[230:233], v[234:249]
	ds_read2_b64 v[194:197], v178 offset0:56 offset1:58
	ds_read2_b64 v[218:221], v250 offset0:88 offset1:90
	s_nop 0
	v_cvt_pk_bf16_f32 v230, v106, v107
	v_cvt_pk_bf16_f32 v231, v108, v109
	v_cvt_pk_bf16_f32 v232, v110, v111
	v_cvt_pk_bf16_f32 v233, v112, v113
	s_waitcnt lgkmcnt(2)
	s_nop 1
	v_mfma_f32_32x32x16_bf16 v[130:145], v[222:225], v[230:233], v[130:145]
	v_mfma_f32_32x32x16_bf16 v[234:249], v[226:229], v[230:233], v[234:249]
	ds_read2_b64 v[222:225], v178 offset0:60 offset1:62
	ds_read2_b64 v[226:229], v250 offset0:92 offset1:94
	s_nop 0
	v_cvt_pk_bf16_f32 v230, v114, v115
	v_cvt_pk_bf16_f32 v231, v116, v117
	v_cvt_pk_bf16_f32 v232, v118, v119
	v_cvt_pk_bf16_f32 v233, v120, v121
	s_waitcnt lgkmcnt(2)
	s_nop 1
	v_mfma_f32_32x32x16_bf16 v[130:145], v[194:197], v[230:233], v[130:145]
	v_mfma_f32_32x32x16_bf16 v[234:249], v[218:221], v[230:233], v[234:249]
	s_nop 0
	v_cvt_pk_bf16_f32 v230, v122, v123
	v_cvt_pk_bf16_f32 v231, v124, v125
	v_cvt_pk_bf16_f32 v232, v126, v127
	v_cvt_pk_bf16_f32 v233, v128, v129
	s_waitcnt lgkmcnt(0)
	s_nop 1
	v_mfma_f32_32x32x16_bf16 v[130:145], v[222:225], v[230:233], v[130:145]
	v_mfma_f32_32x32x16_bf16 v[234:249], v[226:229], v[230:233], v[234:249]
	v_or_b32_e32 v172, v168, v174
	v_ashrrev_i32_e32 v173, 31, v172
	v_lshlrev_b64 v[172:173], 12, v[172:173]
	s_mov_b32 s100, 0xaaaaaaaa
	s_mov_b32 s101, 0xaaaaaaaa
	v_and_b32_e32 v220, 1, v189
	v_mul_u32_u24_e32 v220, 0xffe, v220
	v_mov_b32_e32 v221, 0
	v_lshl_add_u64 v[218:219], v[170:171], 0, v[172:173]
	v_lshl_add_u64 v[218:219], v[218:219], 0, v[220:221]
	s_mov_b32 s7, 0
	s_nop 7
	v_fma_f32 v222, 0, v192, v153
	v_add_f32_e32 v223, v153, v192
	v_exp_f32_e32 v222, v222
	v_exp_f32_e32 v223, v223
	s_nop 0
	v_mul_f32_e32 v222, v222, v130
	v_mul_f32_e32 v223, v223, v131
	s_nop 1
	v_mov_b32_dpp v224, v222 quad_perm:[1,0,3,2] row_mask:0xf bank_mask:0xf
	v_mov_b32_dpp v225, v223 quad_perm:[1,0,3,2] row_mask:0xf bank_mask:0xf
	v_cndmask_b32_e64 v226, v222, v225, s[100:101]
	v_cndmask_b32_e64 v227, v224, v223, s[100:101]
	v_cvt_pk_bf16_f32 v226, v226, v227
	s_mov_b32 s6, 0x0
	v_lshl_add_u64 v[228:229], v[218:219], 0, s[6:7]
	global_store_dword v[228:229], v226, off
	v_fma_f32 v222, 2.0, v192, v153
	v_fmamk_f32 v223, v192, 0x40400000, v153
	v_exp_f32_e32 v222, v222
	v_exp_f32_e32 v223, v223
	s_nop 0
	v_mul_f32_e32 v222, v222, v132
	v_mul_f32_e32 v223, v223, v133
	s_nop 1
	v_mov_b32_dpp v224, v222 quad_perm:[1,0,3,2] row_mask:0xf bank_mask:0xf
	v_mov_b32_dpp v225, v223 quad_perm:[1,0,3,2] row_mask:0xf bank_mask:0xf
	v_cndmask_b32_e64 v226, v222, v225, s[100:101]
	v_cndmask_b32_e64 v227, v224, v223, s[100:101]
	v_cvt_pk_bf16_f32 v226, v226, v227
	s_mov_b32 s6, 0x2000
	v_lshl_add_u64 v[228:229], v[218:219], 0, s[6:7]
	global_store_dword v[228:229], v226, off
	v_fmamk_f32 v222, v192, 0x41000000, v153
	v_fmamk_f32 v223, v192, 0x41100000, v153
	v_exp_f32_e32 v222, v222
	v_exp_f32_e32 v223, v223
	s_nop 0
	v_mul_f32_e32 v222, v222, v134
	v_mul_f32_e32 v223, v223, v135
	s_nop 1
	v_mov_b32_dpp v224, v222 quad_perm:[1,0,3,2] row_mask:0xf bank_mask:0xf
	v_mov_b32_dpp v225, v223 quad_perm:[1,0,3,2] row_mask:0xf bank_mask:0xf
	v_cndmask_b32_e64 v226, v222, v225, s[100:101]
	v_cndmask_b32_e64 v227, v224, v223, s[100:101]
	v_cvt_pk_bf16_f32 v226, v226, v227
	s_mov_b32 s6, 0x8000
	v_lshl_add_u64 v[228:229], v[218:219], 0, s[6:7]
	global_store_dword v[228:229], v226, off
	v_fmamk_f32 v222, v192, 0x41200000, v153
	v_fmamk_f32 v223, v192, 0x41300000, v153
	v_exp_f32_e32 v222, v222
	v_exp_f32_e32 v223, v223
	s_nop 0
	v_mul_f32_e32 v222, v222, v136
	v_mul_f32_e32 v223, v223, v137
	s_nop 1
	v_mov_b32_dpp v224, v222 quad_perm:[1,0,3,2] row_mask:0xf bank_mask:0xf
	v_mov_b32_dpp v225, v223 quad_perm:[1,0,3,2] row_mask:0xf bank_mask:0xf
	v_cndmask_b32_e64 v226, v222, v225, s[100:101]
	v_cndmask_b32_e64 v227, v224, v223, s[100:101]
	v_cvt_pk_bf16_f32 v226, v226, v227
	s_mov_b32 s6, 0xa000
	v_lshl_add_u64 v[228:229], v[218:219], 0, s[6:7]
	global_store_dword v[228:229], v226, off
	v_fmamk_f32 v222, v192, 0x41800000, v153
	v_fmamk_f32 v223, v192, 0x41880000, v153
	v_exp_f32_e32 v222, v222
	v_exp_f32_e32 v223, v223
	s_nop 0
	v_mul_f32_e32 v222, v222, v138
	v_mul_f32_e32 v223, v223, v139
	s_nop 1
	v_mov_b32_dpp v224, v222 quad_perm:[1,0,3,2] row_mask:0xf bank_mask:0xf
	v_mov_b32_dpp v225, v223 quad_perm:[1,0,3,2] row_mask:0xf bank_mask:0xf
	v_cndmask_b32_e64 v226, v222, v225, s[100:101]
	v_cndmask_b32_e64 v227, v224, v223, s[100:101]
	v_cvt_pk_bf16_f32 v226, v226, v227
	s_mov_b32 s6, 0x10000
	v_lshl_add_u64 v[228:229], v[218:219], 0, s[6:7]
	global_store_dword v[228:229], v226, off
	v_fmamk_f32 v222, v192, 0x41900000, v153
	v_fmamk_f32 v223, v192, 0x41980000, v153
	v_exp_f32_e32 v222, v222
	v_exp_f32_e32 v223, v223
	s_nop 0
	v_mul_f32_e32 v222, v222, v140
	v_mul_f32_e32 v223, v223, v141
	s_nop 1
	v_mov_b32_dpp v224, v222 quad_perm:[1,0,3,2] row_mask:0xf bank_mask:0xf
	v_mov_b32_dpp v225, v223 quad_perm:[1,0,3,2] row_mask:0xf bank_mask:0xf
	v_cndmask_b32_e64 v226, v222, v225, s[100:101]
	v_cndmask_b32_e64 v227, v224, v223, s[100:101]
	v_cvt_pk_bf16_f32 v226, v226, v227
	s_mov_b32 s6, 0x12000
	v_lshl_add_u64 v[228:229], v[218:219], 0, s[6:7]
	global_store_dword v[228:229], v226, off
	v_fmamk_f32 v222, v192, 0x41c00000, v153
	v_fmamk_f32 v223, v192, 0x41c80000, v153
	v_exp_f32_e32 v222, v222
	v_exp_f32_e32 v223, v223
	s_nop 0
	v_mul_f32_e32 v222, v222, v142
	v_mul_f32_e32 v223, v223, v143
	s_nop 1
	v_mov_b32_dpp v224, v222 quad_perm:[1,0,3,2] row_mask:0xf bank_mask:0xf
	v_mov_b32_dpp v225, v223 quad_perm:[1,0,3,2] row_mask:0xf bank_mask:0xf
	v_cndmask_b32_e64 v226, v222, v225, s[100:101]
	v_cndmask_b32_e64 v227, v224, v223, s[100:101]
	v_cvt_pk_bf16_f32 v226, v226, v227
	s_mov_b32 s6, 0x18000
	v_lshl_add_u64 v[228:229], v[218:219], 0, s[6:7]
	global_store_dword v[228:229], v226, off
	v_fmamk_f32 v222, v192, 0x41d00000, v153
	v_fmamk_f32 v223, v192, 0x41d80000, v153
	v_exp_f32_e32 v222, v222
	v_exp_f32_e32 v223, v223
	s_nop 0
	v_mul_f32_e32 v222, v222, v144
	v_mul_f32_e32 v223, v223, v145
	s_nop 1
	v_mov_b32_dpp v224, v222 quad_perm:[1,0,3,2] row_mask:0xf bank_mask:0xf
	v_mov_b32_dpp v225, v223 quad_perm:[1,0,3,2] row_mask:0xf bank_mask:0xf
	v_cndmask_b32_e64 v226, v222, v225, s[100:101]
	v_cndmask_b32_e64 v227, v224, v223, s[100:101]
	v_cvt_pk_bf16_f32 v226, v226, v227
	s_mov_b32 s6, 0x1a000
	v_lshl_add_u64 v[228:229], v[218:219], 0, s[6:7]
	global_store_dword v[228:229], v226, off
	v_mov_b32_e32 v130, v234
	v_mov_b32_e32 v131, v235
	v_mov_b32_e32 v132, v236
	v_mov_b32_e32 v133, v237
	v_mov_b32_e32 v134, v238
	v_mov_b32_e32 v135, v239
	v_mov_b32_e32 v136, v240
	v_mov_b32_e32 v137, v241
	v_mov_b32_e32 v138, v242
	v_mov_b32_e32 v139, v243
	v_mov_b32_e32 v140, v244
	v_mov_b32_e32 v141, v245
	v_mov_b32_e32 v142, v246
	v_mov_b32_e32 v143, v247
	v_mov_b32_e32 v144, v248
	v_mov_b32_e32 v145, v249
	s_mov_b32 s100, 0xaaaaaaaa
	s_mov_b32 s101, 0xaaaaaaaa
	v_and_b32_e32 v220, 1, v189
	v_mul_u32_u24_e32 v220, 0xffe, v220
	v_mov_b32_e32 v221, 0
	v_lshl_add_u64 v[218:219], v[170:171], 0, v[172:173]
	v_lshl_add_u64 v[218:219], v[218:219], 0, v[220:221]
	s_mov_b32 s7, 0
	s_nop 7
	v_fmamk_f32 v222, v192, 0x42000000, v153
	v_fmamk_f32 v223, v192, 0x42040000, v153
	v_exp_f32_e32 v222, v222
	v_exp_f32_e32 v223, v223
	s_nop 0
	v_mul_f32_e32 v222, v222, v130
	v_mul_f32_e32 v223, v223, v131
	s_nop 1
	v_mov_b32_dpp v224, v222 quad_perm:[1,0,3,2] row_mask:0xf bank_mask:0xf
	v_mov_b32_dpp v225, v223 quad_perm:[1,0,3,2] row_mask:0xf bank_mask:0xf
	v_cndmask_b32_e64 v226, v222, v225, s[100:101]
	v_cndmask_b32_e64 v227, v224, v223, s[100:101]
	v_cvt_pk_bf16_f32 v226, v226, v227
	s_mov_b32 s6, 0x20000
	v_lshl_add_u64 v[228:229], v[218:219], 0, s[6:7]
	global_store_dword v[228:229], v226, off
	v_fmamk_f32 v222, v192, 0x42080000, v153
	v_fmamk_f32 v223, v192, 0x420c0000, v153
	v_exp_f32_e32 v222, v222
	v_exp_f32_e32 v223, v223
	s_nop 0
	v_mul_f32_e32 v222, v222, v132
	v_mul_f32_e32 v223, v223, v133
	s_nop 1
	v_mov_b32_dpp v224, v222 quad_perm:[1,0,3,2] row_mask:0xf bank_mask:0xf
	v_mov_b32_dpp v225, v223 quad_perm:[1,0,3,2] row_mask:0xf bank_mask:0xf
	v_cndmask_b32_e64 v226, v222, v225, s[100:101]
	v_cndmask_b32_e64 v227, v224, v223, s[100:101]
	v_cvt_pk_bf16_f32 v226, v226, v227
	s_mov_b32 s6, 0x22000
	v_lshl_add_u64 v[228:229], v[218:219], 0, s[6:7]
	global_store_dword v[228:229], v226, off
	v_fmamk_f32 v222, v192, 0x42200000, v153
	v_fmamk_f32 v223, v192, 0x42240000, v153
	v_exp_f32_e32 v222, v222
	v_exp_f32_e32 v223, v223
	s_nop 0
	v_mul_f32_e32 v222, v222, v134
	v_mul_f32_e32 v223, v223, v135
	s_nop 1
	v_mov_b32_dpp v224, v222 quad_perm:[1,0,3,2] row_mask:0xf bank_mask:0xf
	v_mov_b32_dpp v225, v223 quad_perm:[1,0,3,2] row_mask:0xf bank_mask:0xf
	v_cndmask_b32_e64 v226, v222, v225, s[100:101]
	v_cndmask_b32_e64 v227, v224, v223, s[100:101]
	v_cvt_pk_bf16_f32 v226, v226, v227
	s_mov_b32 s6, 0x28000
	v_lshl_add_u64 v[228:229], v[218:219], 0, s[6:7]
	global_store_dword v[228:229], v226, off
	v_fmamk_f32 v222, v192, 0x42280000, v153
	v_fmamk_f32 v223, v192, 0x422c0000, v153
	v_exp_f32_e32 v222, v222
	v_exp_f32_e32 v223, v223
	s_nop 0
	v_mul_f32_e32 v222, v222, v136
	v_mul_f32_e32 v223, v223, v137
	s_nop 1
	v_mov_b32_dpp v224, v222 quad_perm:[1,0,3,2] row_mask:0xf bank_mask:0xf
	v_mov_b32_dpp v225, v223 quad_perm:[1,0,3,2] row_mask:0xf bank_mask:0xf
	v_cndmask_b32_e64 v226, v222, v225, s[100:101]
	v_cndmask_b32_e64 v227, v224, v223, s[100:101]
	v_cvt_pk_bf16_f32 v226, v226, v227
	s_mov_b32 s6, 0x2a000
	v_lshl_add_u64 v[228:229], v[218:219], 0, s[6:7]
	global_store_dword v[228:229], v226, off
	v_fmamk_f32 v222, v192, 0x42400000, v153
	v_fmamk_f32 v223, v192, 0x42440000, v153
	v_exp_f32_e32 v222, v222
	v_exp_f32_e32 v223, v223
	s_nop 0
	v_mul_f32_e32 v222, v222, v138
	v_mul_f32_e32 v223, v223, v139
	s_nop 1
	v_mov_b32_dpp v224, v222 quad_perm:[1,0,3,2] row_mask:0xf bank_mask:0xf
	v_mov_b32_dpp v225, v223 quad_perm:[1,0,3,2] row_mask:0xf bank_mask:0xf
	v_cndmask_b32_e64 v226, v222, v225, s[100:101]
	v_cndmask_b32_e64 v227, v224, v223, s[100:101]
	v_cvt_pk_bf16_f32 v226, v226, v227
	s_mov_b32 s6, 0x30000
	v_lshl_add_u64 v[228:229], v[218:219], 0, s[6:7]
	global_store_dword v[228:229], v226, off
	v_fmamk_f32 v222, v192, 0x42480000, v153
	v_fmamk_f32 v223, v192, 0x424c0000, v153
	v_exp_f32_e32 v222, v222
	v_exp_f32_e32 v223, v223
	s_nop 0
	v_mul_f32_e32 v222, v222, v140
	v_mul_f32_e32 v223, v223, v141
	s_nop 1
	v_mov_b32_dpp v224, v222 quad_perm:[1,0,3,2] row_mask:0xf bank_mask:0xf
	v_mov_b32_dpp v225, v223 quad_perm:[1,0,3,2] row_mask:0xf bank_mask:0xf
	v_cndmask_b32_e64 v226, v222, v225, s[100:101]
	v_cndmask_b32_e64 v227, v224, v223, s[100:101]
	v_cvt_pk_bf16_f32 v226, v226, v227
	s_mov_b32 s6, 0x32000
	v_lshl_add_u64 v[228:229], v[218:219], 0, s[6:7]
	global_store_dword v[228:229], v226, off
	v_fmamk_f32 v222, v192, 0x42600000, v153
	v_fmamk_f32 v223, v192, 0x42640000, v153
	v_exp_f32_e32 v222, v222
	v_exp_f32_e32 v223, v223
	s_nop 0
	v_mul_f32_e32 v222, v222, v142
	v_mul_f32_e32 v223, v223, v143
	s_nop 1
	v_mov_b32_dpp v224, v222 quad_perm:[1,0,3,2] row_mask:0xf bank_mask:0xf
	v_mov_b32_dpp v225, v223 quad_perm:[1,0,3,2] row_mask:0xf bank_mask:0xf
	v_cndmask_b32_e64 v226, v222, v225, s[100:101]
	v_cndmask_b32_e64 v227, v224, v223, s[100:101]
	v_cvt_pk_bf16_f32 v226, v226, v227
	s_mov_b32 s6, 0x38000
	v_lshl_add_u64 v[228:229], v[218:219], 0, s[6:7]
	global_store_dword v[228:229], v226, off
	v_fmamk_f32 v222, v192, 0x42680000, v153
	v_fmamk_f32 v223, v192, 0x426c0000, v153
	v_exp_f32_e32 v222, v222
	v_exp_f32_e32 v223, v223
	s_nop 0
	v_mul_f32_e32 v222, v222, v144
	v_mul_f32_e32 v223, v223, v145
	s_nop 1
	v_mov_b32_dpp v224, v222 quad_perm:[1,0,3,2] row_mask:0xf bank_mask:0xf
	v_mov_b32_dpp v225, v223 quad_perm:[1,0,3,2] row_mask:0xf bank_mask:0xf
	v_cndmask_b32_e64 v226, v222, v225, s[100:101]
	v_cndmask_b32_e64 v227, v224, v223, s[100:101]
	v_cvt_pk_bf16_f32 v226, v226, v227
	s_mov_b32 s6, 0x3a000
	v_lshl_add_u64 v[228:229], v[218:219], 0, s[6:7]
	global_store_dword v[228:229], v226, off
	v_add_u32_e32 v250, 0xc000, v178
	v_add_u32_e32 v251, 0x8000, v178
	ds_read2_b64 v[194:197], v251 offset0:64 offset1:66
	ds_read2_b64 v[218:221], v250 offset0:96 offset1:98
	ds_read2_b64 v[222:225], v251 offset0:68 offset1:70
	ds_read2_b64 v[226:229], v250 offset0:100 offset1:102
	s_nop 0
	v_cvt_pk_bf16_f32 v230, v2, v3
	v_cvt_pk_bf16_f32 v231, v4, v5
	v_cvt_pk_bf16_f32 v232, v6, v7
	v_cvt_pk_bf16_f32 v233, v8, v9
	s_waitcnt lgkmcnt(2)
	s_nop 1
	v_mfma_f32_32x32x16_bf16 v[130:145], v[194:197], v[230:233], 0
	v_mfma_f32_32x32x16_bf16 v[234:249], v[218:221], v[230:233], 0
	ds_read2_b64 v[194:197], v251 offset0:72 offset1:74
	ds_read2_b64 v[218:221], v250 offset0:104 offset1:106
	s_nop 0
	v_cvt_pk_bf16_f32 v230, v10, v11
	v_cvt_pk_bf16_f32 v231, v12, v13
	v_cvt_pk_bf16_f32 v232, v14, v15
	v_cvt_pk_bf16_f32 v233, v16, v17
	s_waitcnt lgkmcnt(2)
	s_nop 1
	v_mfma_f32_32x32x16_bf16 v[130:145], v[222:225], v[230:233], v[130:145]
	v_mfma_f32_32x32x16_bf16 v[234:249], v[226:229], v[230:233], v[234:249]
	ds_read2_b64 v[222:225], v251 offset0:76 offset1:78
	ds_read2_b64 v[226:229], v250 offset0:108 offset1:110
	s_nop 0
	v_cvt_pk_bf16_f32 v230, v18, v19
	v_cvt_pk_bf16_f32 v231, v20, v21
	v_cvt_pk_bf16_f32 v232, v22, v23
	v_cvt_pk_bf16_f32 v233, v24, v25
	s_waitcnt lgkmcnt(2)
	s_nop 1
	v_mfma_f32_32x32x16_bf16 v[130:145], v[194:197], v[230:233], v[130:145]
	v_mfma_f32_32x32x16_bf16 v[234:249], v[218:221], v[230:233], v[234:249]
	ds_read2_b64 v[194:197], v251 offset0:80 offset1:82
	ds_read2_b64 v[218:221], v250 offset0:112 offset1:114
	s_nop 0
	v_cvt_pk_bf16_f32 v230, v26, v27
	v_cvt_pk_bf16_f32 v231, v28, v29
	v_cvt_pk_bf16_f32 v232, v30, v31
	v_cvt_pk_bf16_f32 v233, v32, v33
	s_waitcnt lgkmcnt(2)
	s_nop 1
	v_mfma_f32_32x32x16_bf16 v[130:145], v[222:225], v[230:233], v[130:145]
	v_mfma_f32_32x32x16_bf16 v[234:249], v[226:229], v[230:233], v[234:249]
	ds_read2_b64 v[222:225], v251 offset0:84 offset1:86
	ds_read2_b64 v[226:229], v250 offset0:116 offset1:118
	s_nop 0
	v_cvt_pk_bf16_f32 v230, v34, v35
	v_cvt_pk_bf16_f32 v231, v36, v37
	v_cvt_pk_bf16_f32 v232, v38, v39
	v_cvt_pk_bf16_f32 v233, v40, v41
	s_waitcnt lgkmcnt(2)
	s_nop 1
	v_mfma_f32_32x32x16_bf16 v[130:145], v[194:197], v[230:233], v[130:145]
	v_mfma_f32_32x32x16_bf16 v[234:249], v[218:221], v[230:233], v[234:249]
	ds_read2_b64 v[194:197], v251 offset0:88 offset1:90
	ds_read2_b64 v[218:221], v250 offset0:120 offset1:122
	s_nop 0
	v_cvt_pk_bf16_f32 v230, v42, v43
	v_cvt_pk_bf16_f32 v231, v44, v45
	v_cvt_pk_bf16_f32 v232, v46, v47
	v_cvt_pk_bf16_f32 v233, v48, v49
	s_waitcnt lgkmcnt(2)
	s_nop 1
	v_mfma_f32_32x32x16_bf16 v[130:145], v[222:225], v[230:233], v[130:145]
	v_mfma_f32_32x32x16_bf16 v[234:249], v[226:229], v[230:233], v[234:249]
	ds_read2_b64 v[222:225], v251 offset0:92 offset1:94
	ds_read2_b64 v[226:229], v250 offset0:124 offset1:126
	s_nop 0
	v_cvt_pk_bf16_f32 v230, v50, v51
	v_cvt_pk_bf16_f32 v231, v52, v53
	v_cvt_pk_bf16_f32 v232, v54, v55
	v_cvt_pk_bf16_f32 v233, v56, v57
	s_waitcnt lgkmcnt(2)
	s_nop 1
	v_mfma_f32_32x32x16_bf16 v[130:145], v[194:197], v[230:233], v[130:145]
	v_mfma_f32_32x32x16_bf16 v[234:249], v[218:221], v[230:233], v[234:249]
	ds_read2_b64 v[194:197], v251 offset0:96 offset1:98
	ds_read2_b64 v[218:221], v250 offset0:128 offset1:130
	s_nop 0
	v_cvt_pk_bf16_f32 v230, v58, v59
	v_cvt_pk_bf16_f32 v231, v60, v61
	v_cvt_pk_bf16_f32 v232, v62, v63
	v_cvt_pk_bf16_f32 v233, v64, v65
	s_waitcnt lgkmcnt(2)
	s_nop 1
	v_mfma_f32_32x32x16_bf16 v[130:145], v[222:225], v[230:233], v[130:145]
	v_mfma_f32_32x32x16_bf16 v[234:249], v[226:229], v[230:233], v[234:249]
	ds_read2_b64 v[222:225], v251 offset0:100 offset1:102
	ds_read2_b64 v[226:229], v250 offset0:132 offset1:134
	s_nop 0
	v_cvt_pk_bf16_f32 v230, v66, v67
	v_cvt_pk_bf16_f32 v231, v68, v69
	v_cvt_pk_bf16_f32 v232, v70, v71
	v_cvt_pk_bf16_f32 v233, v72, v73
	s_waitcnt lgkmcnt(2)
	s_nop 1
	v_mfma_f32_32x32x16_bf16 v[130:145], v[194:197], v[230:233], v[130:145]
	v_mfma_f32_32x32x16_bf16 v[234:249], v[218:221], v[230:233], v[234:249]
	ds_read2_b64 v[194:197], v251 offset0:104 offset1:106
	ds_read2_b64 v[218:221], v250 offset0:136 offset1:138
	s_nop 0
	v_cvt_pk_bf16_f32 v230, v74, v75
	v_cvt_pk_bf16_f32 v231, v76, v77
	v_cvt_pk_bf16_f32 v232, v78, v79
	v_cvt_pk_bf16_f32 v233, v80, v81
	s_waitcnt lgkmcnt(2)
	s_nop 1
	v_mfma_f32_32x32x16_bf16 v[130:145], v[222:225], v[230:233], v[130:145]
	v_mfma_f32_32x32x16_bf16 v[234:249], v[226:229], v[230:233], v[234:249]
	ds_read2_b64 v[222:225], v251 offset0:108 offset1:110
	ds_read2_b64 v[226:229], v250 offset0:140 offset1:142
	s_nop 0
	v_cvt_pk_bf16_f32 v230, v82, v83
	v_cvt_pk_bf16_f32 v231, v84, v85
	v_cvt_pk_bf16_f32 v232, v86, v87
	v_cvt_pk_bf16_f32 v233, v88, v89
	s_waitcnt lgkmcnt(2)
	s_nop 1
	v_mfma_f32_32x32x16_bf16 v[130:145], v[194:197], v[230:233], v[130:145]
	v_mfma_f32_32x32x16_bf16 v[234:249], v[218:221], v[230:233], v[234:249]
	ds_read2_b64 v[194:197], v251 offset0:112 offset1:114
	ds_read2_b64 v[218:221], v250 offset0:144 offset1:146
	s_nop 0
	v_cvt_pk_bf16_f32 v230, v90, v91
	v_cvt_pk_bf16_f32 v231, v92, v93
	v_cvt_pk_bf16_f32 v232, v94, v95
	v_cvt_pk_bf16_f32 v233, v96, v97
	s_waitcnt lgkmcnt(2)
	s_nop 1
	v_mfma_f32_32x32x16_bf16 v[130:145], v[222:225], v[230:233], v[130:145]
	v_mfma_f32_32x32x16_bf16 v[234:249], v[226:229], v[230:233], v[234:249]
	ds_read2_b64 v[222:225], v251 offset0:116 offset1:118
	ds_read2_b64 v[226:229], v250 offset0:148 offset1:150
	s_nop 0
	v_cvt_pk_bf16_f32 v230, v98, v99
	v_cvt_pk_bf16_f32 v231, v100, v101
	v_cvt_pk_bf16_f32 v232, v102, v103
	v_cvt_pk_bf16_f32 v233, v104, v105
	s_waitcnt lgkmcnt(2)
	s_nop 1
	v_mfma_f32_32x32x16_bf16 v[130:145], v[194:197], v[230:233], v[130:145]
	v_mfma_f32_32x32x16_bf16 v[234:249], v[218:221], v[230:233], v[234:249]
	ds_read2_b64 v[194:197], v251 offset0:120 offset1:122
	ds_read2_b64 v[218:221], v250 offset0:152 offset1:154
	s_nop 0
	v_cvt_pk_bf16_f32 v230, v106, v107
	v_cvt_pk_bf16_f32 v231, v108, v109
	v_cvt_pk_bf16_f32 v232, v110, v111
	v_cvt_pk_bf16_f32 v233, v112, v113
	s_waitcnt lgkmcnt(2)
	s_nop 1
	v_mfma_f32_32x32x16_bf16 v[130:145], v[222:225], v[230:233], v[130:145]
	v_mfma_f32_32x32x16_bf16 v[234:249], v[226:229], v[230:233], v[234:249]
	ds_read2_b64 v[222:225], v251 offset0:124 offset1:126
	ds_read2_b64 v[226:229], v250 offset0:156 offset1:158
	s_nop 0
	v_cvt_pk_bf16_f32 v230, v114, v115
	v_cvt_pk_bf16_f32 v231, v116, v117
	v_cvt_pk_bf16_f32 v232, v118, v119
	v_cvt_pk_bf16_f32 v233, v120, v121
	s_waitcnt lgkmcnt(2)
	s_nop 1
	v_mfma_f32_32x32x16_bf16 v[130:145], v[194:197], v[230:233], v[130:145]
	v_mfma_f32_32x32x16_bf16 v[234:249], v[218:221], v[230:233], v[234:249]
	s_nop 0
	v_cvt_pk_bf16_f32 v230, v122, v123
	v_cvt_pk_bf16_f32 v231, v124, v125
	v_cvt_pk_bf16_f32 v232, v126, v127
	v_cvt_pk_bf16_f32 v233, v128, v129
	s_waitcnt lgkmcnt(0)
	s_nop 1
	v_mfma_f32_32x32x16_bf16 v[130:145], v[222:225], v[230:233], v[130:145]
	v_mfma_f32_32x32x16_bf16 v[234:249], v[226:229], v[230:233], v[234:249]
	s_mov_b32 s100, 0xaaaaaaaa
	s_mov_b32 s101, 0xaaaaaaaa
	v_and_b32_e32 v220, 1, v189
	v_mul_u32_u24_e32 v220, 0xffe, v220
	v_mov_b32_e32 v221, 0
	v_lshl_add_u64 v[218:219], v[170:171], 0, v[172:173]
	v_lshl_add_u64 v[218:219], v[218:219], 0, v[220:221]
	s_mov_b32 s7, 0
	s_nop 7
	v_fmamk_f32 v222, v192, 0x42800000, v153
	v_fmamk_f32 v223, v192, 0x42820000, v153
	v_exp_f32_e32 v222, v222
	v_exp_f32_e32 v223, v223
	s_nop 0
	v_mul_f32_e32 v222, v222, v130
	v_mul_f32_e32 v223, v223, v131
	s_nop 1
	v_mov_b32_dpp v224, v222 quad_perm:[1,0,3,2] row_mask:0xf bank_mask:0xf
	v_mov_b32_dpp v225, v223 quad_perm:[1,0,3,2] row_mask:0xf bank_mask:0xf
	v_cndmask_b32_e64 v226, v222, v225, s[100:101]
	v_cndmask_b32_e64 v227, v224, v223, s[100:101]
	v_cvt_pk_bf16_f32 v226, v226, v227
	s_mov_b32 s6, 0x40000
	v_lshl_add_u64 v[228:229], v[218:219], 0, s[6:7]
	global_store_dword v[228:229], v226, off
	v_fmamk_f32 v222, v192, 0x42840000, v153
	v_fmamk_f32 v223, v192, 0x42860000, v153
	v_exp_f32_e32 v222, v222
	v_exp_f32_e32 v223, v223
	s_nop 0
	v_mul_f32_e32 v222, v222, v132
	v_mul_f32_e32 v223, v223, v133
	s_nop 1
	v_mov_b32_dpp v224, v222 quad_perm:[1,0,3,2] row_mask:0xf bank_mask:0xf
	v_mov_b32_dpp v225, v223 quad_perm:[1,0,3,2] row_mask:0xf bank_mask:0xf
	v_cndmask_b32_e64 v226, v222, v225, s[100:101]
	v_cndmask_b32_e64 v227, v224, v223, s[100:101]
	v_cvt_pk_bf16_f32 v226, v226, v227
	s_mov_b32 s6, 0x42000
	v_lshl_add_u64 v[228:229], v[218:219], 0, s[6:7]
	global_store_dword v[228:229], v226, off
	v_fmamk_f32 v222, v192, 0x42900000, v153
	v_fmamk_f32 v223, v192, 0x42920000, v153
	v_exp_f32_e32 v222, v222
	v_exp_f32_e32 v223, v223
	s_nop 0
	v_mul_f32_e32 v222, v222, v134
	v_mul_f32_e32 v223, v223, v135
	s_nop 1
	v_mov_b32_dpp v224, v222 quad_perm:[1,0,3,2] row_mask:0xf bank_mask:0xf
	v_mov_b32_dpp v225, v223 quad_perm:[1,0,3,2] row_mask:0xf bank_mask:0xf
	v_cndmask_b32_e64 v226, v222, v225, s[100:101]
	v_cndmask_b32_e64 v227, v224, v223, s[100:101]
	v_cvt_pk_bf16_f32 v226, v226, v227
	s_mov_b32 s6, 0x48000
	v_lshl_add_u64 v[228:229], v[218:219], 0, s[6:7]
	global_store_dword v[228:229], v226, off
	v_fmamk_f32 v222, v192, 0x42940000, v153
	v_fmamk_f32 v223, v192, 0x42960000, v153
	v_exp_f32_e32 v222, v222
	v_exp_f32_e32 v223, v223
	s_nop 0
	v_mul_f32_e32 v222, v222, v136
	v_mul_f32_e32 v223, v223, v137
	s_nop 1
	v_mov_b32_dpp v224, v222 quad_perm:[1,0,3,2] row_mask:0xf bank_mask:0xf
	v_mov_b32_dpp v225, v223 quad_perm:[1,0,3,2] row_mask:0xf bank_mask:0xf
	v_cndmask_b32_e64 v226, v222, v225, s[100:101]
	v_cndmask_b32_e64 v227, v224, v223, s[100:101]
	v_cvt_pk_bf16_f32 v226, v226, v227
	s_mov_b32 s6, 0x4a000
	v_lshl_add_u64 v[228:229], v[218:219], 0, s[6:7]
	global_store_dword v[228:229], v226, off
	v_fmamk_f32 v222, v192, 0x42a00000, v153
	v_fmamk_f32 v223, v192, 0x42a20000, v153
	v_exp_f32_e32 v222, v222
	v_exp_f32_e32 v223, v223
	s_nop 0
	v_mul_f32_e32 v222, v222, v138
	v_mul_f32_e32 v223, v223, v139
	s_nop 1
	v_mov_b32_dpp v224, v222 quad_perm:[1,0,3,2] row_mask:0xf bank_mask:0xf
	v_mov_b32_dpp v225, v223 quad_perm:[1,0,3,2] row_mask:0xf bank_mask:0xf
	v_cndmask_b32_e64 v226, v222, v225, s[100:101]
	v_cndmask_b32_e64 v227, v224, v223, s[100:101]
	v_cvt_pk_bf16_f32 v226, v226, v227
	s_mov_b32 s6, 0x50000
	v_lshl_add_u64 v[228:229], v[218:219], 0, s[6:7]
	global_store_dword v[228:229], v226, off
	v_fmamk_f32 v222, v192, 0x42a40000, v153
	v_fmamk_f32 v223, v192, 0x42a60000, v153
	v_exp_f32_e32 v222, v222
	v_exp_f32_e32 v223, v223
	s_nop 0
	v_mul_f32_e32 v222, v222, v140
	v_mul_f32_e32 v223, v223, v141
	s_nop 1
	v_mov_b32_dpp v224, v222 quad_perm:[1,0,3,2] row_mask:0xf bank_mask:0xf
	v_mov_b32_dpp v225, v223 quad_perm:[1,0,3,2] row_mask:0xf bank_mask:0xf
	v_cndmask_b32_e64 v226, v222, v225, s[100:101]
	v_cndmask_b32_e64 v227, v224, v223, s[100:101]
	v_cvt_pk_bf16_f32 v226, v226, v227
	s_mov_b32 s6, 0x52000
	v_lshl_add_u64 v[228:229], v[218:219], 0, s[6:7]
	global_store_dword v[228:229], v226, off
	v_fmamk_f32 v222, v192, 0x42b00000, v153
	v_fmamk_f32 v223, v192, 0x42b20000, v153
	v_exp_f32_e32 v222, v222
	v_exp_f32_e32 v223, v223
	s_nop 0
	v_mul_f32_e32 v222, v222, v142
	v_mul_f32_e32 v223, v223, v143
	s_nop 1
	v_mov_b32_dpp v224, v222 quad_perm:[1,0,3,2] row_mask:0xf bank_mask:0xf
	v_mov_b32_dpp v225, v223 quad_perm:[1,0,3,2] row_mask:0xf bank_mask:0xf
	v_cndmask_b32_e64 v226, v222, v225, s[100:101]
	v_cndmask_b32_e64 v227, v224, v223, s[100:101]
	v_cvt_pk_bf16_f32 v226, v226, v227
	s_mov_b32 s6, 0x58000
	v_lshl_add_u64 v[228:229], v[218:219], 0, s[6:7]
	global_store_dword v[228:229], v226, off
	v_fmamk_f32 v222, v192, 0x42b40000, v153
	v_fmamk_f32 v223, v192, 0x42b60000, v153
	v_exp_f32_e32 v222, v222
	v_exp_f32_e32 v223, v223
	s_nop 0
	v_mul_f32_e32 v222, v222, v144
	v_mul_f32_e32 v223, v223, v145
	s_nop 1
	v_mov_b32_dpp v224, v222 quad_perm:[1,0,3,2] row_mask:0xf bank_mask:0xf
	v_mov_b32_dpp v225, v223 quad_perm:[1,0,3,2] row_mask:0xf bank_mask:0xf
	v_cndmask_b32_e64 v226, v222, v225, s[100:101]
	v_cndmask_b32_e64 v227, v224, v223, s[100:101]
	v_cvt_pk_bf16_f32 v226, v226, v227
	s_mov_b32 s6, 0x5a000
	v_lshl_add_u64 v[228:229], v[218:219], 0, s[6:7]
	global_store_dword v[228:229], v226, off
	v_mov_b32_e32 v130, v234
	v_mov_b32_e32 v131, v235
	v_mov_b32_e32 v132, v236
	v_mov_b32_e32 v133, v237
	v_mov_b32_e32 v134, v238
	v_mov_b32_e32 v135, v239
	v_mov_b32_e32 v136, v240
	v_mov_b32_e32 v137, v241
	v_mov_b32_e32 v138, v242
	v_mov_b32_e32 v139, v243
	v_mov_b32_e32 v140, v244
	v_mov_b32_e32 v141, v245
	v_mov_b32_e32 v142, v246
	v_mov_b32_e32 v143, v247
	v_mov_b32_e32 v144, v248
	v_mov_b32_e32 v145, v249
	s_mov_b32 s100, 0xaaaaaaaa
	s_mov_b32 s101, 0xaaaaaaaa
	v_and_b32_e32 v220, 1, v189
	v_mul_u32_u24_e32 v220, 0xffe, v220
	v_mov_b32_e32 v221, 0
	v_lshl_add_u64 v[218:219], v[170:171], 0, v[172:173]
	v_lshl_add_u64 v[218:219], v[218:219], 0, v[220:221]
	s_mov_b32 s7, 0
	s_nop 7
	v_fmamk_f32 v222, v192, 0x42c00000, v153
	v_fmamk_f32 v223, v192, 0x42c20000, v153
	v_exp_f32_e32 v222, v222
	v_exp_f32_e32 v223, v223
	s_nop 0
	v_mul_f32_e32 v222, v222, v130
	v_mul_f32_e32 v223, v223, v131
	s_nop 1
	v_mov_b32_dpp v224, v222 quad_perm:[1,0,3,2] row_mask:0xf bank_mask:0xf
	v_mov_b32_dpp v225, v223 quad_perm:[1,0,3,2] row_mask:0xf bank_mask:0xf
	v_cndmask_b32_e64 v226, v222, v225, s[100:101]
	v_cndmask_b32_e64 v227, v224, v223, s[100:101]
	v_cvt_pk_bf16_f32 v226, v226, v227
	s_mov_b32 s6, 0x60000
	v_lshl_add_u64 v[228:229], v[218:219], 0, s[6:7]
	global_store_dword v[228:229], v226, off
	v_fmamk_f32 v222, v192, 0x42c40000, v153
	v_fmamk_f32 v223, v192, 0x42c60000, v153
	v_exp_f32_e32 v222, v222
	v_exp_f32_e32 v223, v223
	s_nop 0
	v_mul_f32_e32 v222, v222, v132
	v_mul_f32_e32 v223, v223, v133
	s_nop 1
	v_mov_b32_dpp v224, v222 quad_perm:[1,0,3,2] row_mask:0xf bank_mask:0xf
	v_mov_b32_dpp v225, v223 quad_perm:[1,0,3,2] row_mask:0xf bank_mask:0xf
	v_cndmask_b32_e64 v226, v222, v225, s[100:101]
	v_cndmask_b32_e64 v227, v224, v223, s[100:101]
	v_cvt_pk_bf16_f32 v226, v226, v227
	s_mov_b32 s6, 0x62000
	v_lshl_add_u64 v[228:229], v[218:219], 0, s[6:7]
	global_store_dword v[228:229], v226, off
	v_fmamk_f32 v222, v192, 0x42d00000, v153
	v_fmamk_f32 v223, v192, 0x42d20000, v153
	v_exp_f32_e32 v222, v222
	v_exp_f32_e32 v223, v223
	s_nop 0
	v_mul_f32_e32 v222, v222, v134
	v_mul_f32_e32 v223, v223, v135
	s_nop 1
	v_mov_b32_dpp v224, v222 quad_perm:[1,0,3,2] row_mask:0xf bank_mask:0xf
	v_mov_b32_dpp v225, v223 quad_perm:[1,0,3,2] row_mask:0xf bank_mask:0xf
	v_cndmask_b32_e64 v226, v222, v225, s[100:101]
	v_cndmask_b32_e64 v227, v224, v223, s[100:101]
	v_cvt_pk_bf16_f32 v226, v226, v227
	s_mov_b32 s6, 0x68000
	v_lshl_add_u64 v[228:229], v[218:219], 0, s[6:7]
	global_store_dword v[228:229], v226, off
	v_fmamk_f32 v222, v192, 0x42d40000, v153
	v_fmamk_f32 v223, v192, 0x42d60000, v153
	v_exp_f32_e32 v222, v222
	v_exp_f32_e32 v223, v223
	s_nop 0
	v_mul_f32_e32 v222, v222, v136
	v_mul_f32_e32 v223, v223, v137
	s_nop 1
	v_mov_b32_dpp v224, v222 quad_perm:[1,0,3,2] row_mask:0xf bank_mask:0xf
	v_mov_b32_dpp v225, v223 quad_perm:[1,0,3,2] row_mask:0xf bank_mask:0xf
	v_cndmask_b32_e64 v226, v222, v225, s[100:101]
	v_cndmask_b32_e64 v227, v224, v223, s[100:101]
	v_cvt_pk_bf16_f32 v226, v226, v227
	s_mov_b32 s6, 0x6a000
	v_lshl_add_u64 v[228:229], v[218:219], 0, s[6:7]
	global_store_dword v[228:229], v226, off
	v_fmamk_f32 v222, v192, 0x42e00000, v153
	v_fmamk_f32 v223, v192, 0x42e20000, v153
	v_exp_f32_e32 v222, v222
	v_exp_f32_e32 v223, v223
	s_nop 0
	v_mul_f32_e32 v222, v222, v138
	v_mul_f32_e32 v223, v223, v139
	s_nop 1
	v_mov_b32_dpp v224, v222 quad_perm:[1,0,3,2] row_mask:0xf bank_mask:0xf
	v_mov_b32_dpp v225, v223 quad_perm:[1,0,3,2] row_mask:0xf bank_mask:0xf
	v_cndmask_b32_e64 v226, v222, v225, s[100:101]
	v_cndmask_b32_e64 v227, v224, v223, s[100:101]
	v_cvt_pk_bf16_f32 v226, v226, v227
	s_mov_b32 s6, 0x70000
	v_lshl_add_u64 v[228:229], v[218:219], 0, s[6:7]
	global_store_dword v[228:229], v226, off
	v_fmamk_f32 v222, v192, 0x42e40000, v153
	v_fmamk_f32 v223, v192, 0x42e60000, v153
	v_exp_f32_e32 v222, v222
	v_exp_f32_e32 v223, v223
	s_nop 0
	v_mul_f32_e32 v222, v222, v140
	v_mul_f32_e32 v223, v223, v141
	s_nop 1
	v_mov_b32_dpp v224, v222 quad_perm:[1,0,3,2] row_mask:0xf bank_mask:0xf
	v_mov_b32_dpp v225, v223 quad_perm:[1,0,3,2] row_mask:0xf bank_mask:0xf
	v_cndmask_b32_e64 v226, v222, v225, s[100:101]
	v_cndmask_b32_e64 v227, v224, v223, s[100:101]
	v_cvt_pk_bf16_f32 v226, v226, v227
	s_mov_b32 s6, 0x72000
	v_lshl_add_u64 v[228:229], v[218:219], 0, s[6:7]
	global_store_dword v[228:229], v226, off
	v_fmamk_f32 v222, v192, 0x42f00000, v153
	v_fmamk_f32 v223, v192, 0x42f20000, v153
	v_exp_f32_e32 v222, v222
	v_exp_f32_e32 v223, v223
	s_nop 0
	v_mul_f32_e32 v222, v222, v142
	v_mul_f32_e32 v223, v223, v143
	s_nop 1
	v_mov_b32_dpp v224, v222 quad_perm:[1,0,3,2] row_mask:0xf bank_mask:0xf
	v_mov_b32_dpp v225, v223 quad_perm:[1,0,3,2] row_mask:0xf bank_mask:0xf
	v_cndmask_b32_e64 v226, v222, v225, s[100:101]
	v_cndmask_b32_e64 v227, v224, v223, s[100:101]
	v_cvt_pk_bf16_f32 v226, v226, v227
	s_mov_b32 s6, 0x78000
	v_lshl_add_u64 v[228:229], v[218:219], 0, s[6:7]
	global_store_dword v[228:229], v226, off
	v_fmamk_f32 v222, v192, 0x42f40000, v153
	v_fmamk_f32 v223, v192, 0x42f60000, v153
	v_exp_f32_e32 v222, v222
	v_exp_f32_e32 v223, v223
	s_nop 0
	v_mul_f32_e32 v222, v222, v144
	v_mul_f32_e32 v223, v223, v145
	s_nop 1
	v_mov_b32_dpp v224, v222 quad_perm:[1,0,3,2] row_mask:0xf bank_mask:0xf
	v_mov_b32_dpp v225, v223 quad_perm:[1,0,3,2] row_mask:0xf bank_mask:0xf
	v_cndmask_b32_e64 v226, v222, v225, s[100:101]
	v_cndmask_b32_e64 v227, v224, v223, s[100:101]
	v_cvt_pk_bf16_f32 v226, v226, v227
	s_mov_b32 s6, 0x7a000
	v_lshl_add_u64 v[228:229], v[218:219], 0, s[6:7]
	global_store_dword v[228:229], v226, off
	v_mov_b32_e32 v153, v189
	s_waitcnt vmcnt(63) expcnt(7) lgkmcnt(15)
	s_barrier
	v_lshl_add_u64 v[132:133], s[64:65], 0, v[164:165]
	v_lshlrev_b64 v[130:131], 1, v[168:169]
	v_lshlrev_b64 v[226:227], 14, v[166:167]
	v_lshl_add_u64 v[226:227], s[64:65], 0, v[226:227]
	v_lshl_add_u64 v[226:227], v[226:227], 0, v[130:131]
	v_mov_b32_e32 v228, v152
	v_mov_b32_e32 v229, v1
	v_lshl_add_u64 v[226:227], v[226:227], 0, v[228:229]
	s_mov_b64 s[6:7], 0xf640000
	v_lshl_add_u64 v[226:227], v[226:227], 0, s[6:7]
	global_load_dwordx4 v[234:237], v[226:227], off
	global_load_dwordx4 v[238:241], v[226:227], off offset:32
	global_load_dwordx4 v[242:245], v[226:227], off offset:64
	global_load_dwordx4 v[246:249], v[226:227], off offset:96
	v_lshl_add_u64 v[132:133], v[132:133], 0, v[130:131]
	v_lshlrev_b32_e32 v134, 4, v153
	v_and_b32_e32 v144, 0xf0, v134
	v_mov_b32_e32 v145, v1
	v_lshlrev_b32_e32 v134, 10, v153
	v_lshl_add_u64 v[132:133], v[132:133], 0, v[144:145]
	v_and_b32_e32 v134, 0x3c000, v134
	v_mov_b32_e32 v135, v1
	v_lshl_add_u64 v[172:173], v[132:133], 0, v[134:135]
	s_mov_b32 s6, 0xe640000
	v_add_co_u32_e64 v132, s[6:7], s6, v172
	v_bfe_u32 v145, v153, 4, 4
	s_nop 0
	v_addc_co_u32_e64 v133, s[6:7], 0, v173, s[6:7]
	s_mov_b32 s6, 0xe680000
	s_nop 0
	v_add_co_u32_e64 v136, s[6:7], s6, v172
	global_load_dwordx4 v[132:135], v[132:133], off
	s_nop 0
	v_addc_co_u32_e64 v137, s[6:7], 0, v173, s[6:7]
	s_mov_b32 s6, 0xe6c0000
	s_nop 0
	v_add_co_u32_e64 v140, s[6:7], s6, v172
	global_load_dwordx4 v[136:139], v[136:137], off
	s_nop 0
	v_addc_co_u32_e64 v141, s[6:7], 0, v173, s[6:7]
	s_mov_b32 s6, 0xe700000
	s_nop 0
	v_add_co_u32_e64 v168, s[6:7], s6, v172
	global_load_dwordx4 v[140:143], v[140:141], off
	s_nop 0
	v_addc_co_u32_e64 v169, s[6:7], 0, v173, s[6:7]
	s_mov_b32 s6, 0xe740000
	s_nop 0
	v_add_co_u32_e64 v192, s[6:7], s6, v172
	global_load_dwordx4 v[168:171], v[168:169], off
	s_nop 0
	v_addc_co_u32_e64 v193, s[6:7], 0, v173, s[6:7]
	s_mov_b32 s6, 0xe780000
	s_nop 0
	v_add_co_u32_e64 v196, s[6:7], s6, v172
	global_load_dwordx4 v[192:195], v[192:193], off
	s_nop 0
	v_addc_co_u32_e64 v197, s[6:7], 0, v173, s[6:7]
	s_mov_b32 s6, 0xe7c0000
	s_nop 0
	v_add_co_u32_e64 v208, s[6:7], s6, v172
	global_load_dwordx4 v[196:199], v[196:197], off
	s_nop 0
	v_addc_co_u32_e64 v209, s[6:7], 0, v173, s[6:7]
	s_mov_b32 s6, 0xe800000
	global_load_dwordx4 v[218:221], v[208:209], off
	v_add_co_u32_e64 v208, s[6:7], s6, v172
	v_mul_u32_u24_e32 v145, 0x108, v145
	s_nop 0
	v_addc_co_u32_e64 v209, s[6:7], 0, v173, s[6:7]
	global_load_dwordx4 v[222:225], v[208:209], off
	v_add3_u32 v153, v149, v144, v145
	s_waitcnt vmcnt(7)
	ds_write2_b64 v153, v[132:133], v[134:135] offset1:1
	v_add_u32_e32 v132, 0x1080, v153
	s_waitcnt vmcnt(6)
	ds_write2_b64 v132, v[136:137], v[138:139] offset1:1
	v_add_u32_e32 v132, 0x2100, v153
	s_waitcnt vmcnt(5)
	ds_write2_b64 v132, v[140:141], v[142:143] offset1:1
	v_add_u32_e32 v132, 0x3180, v153
	s_waitcnt vmcnt(4)
	ds_write2_b64 v132, v[168:169], v[170:171] offset1:1
	v_add_u32_e32 v132, 0x4200, v153
	s_waitcnt vmcnt(3)
	ds_write2_b64 v132, v[192:193], v[194:195] offset1:1
	v_add_u32_e32 v132, 0x5280, v153
	s_waitcnt vmcnt(2)
	ds_write2_b64 v132, v[196:197], v[198:199] offset1:1
	v_add_u32_e32 v132, 0x6300, v153
	s_waitcnt vmcnt(1)
	ds_write2_b64 v132, v[218:219], v[220:221] offset1:1
	v_add_u32_e32 v132, 0x7380, v153
	s_waitcnt vmcnt(0)
	ds_write2_b64 v132, v[222:223], v[224:225] offset1:1
	s_mov_b32 s6, 0xe840000
	v_add_co_u32_e64 v132, s[6:7], s6, v172
	s_nop 1
	v_addc_co_u32_e64 v133, s[6:7], 0, v173, s[6:7]
	s_mov_b32 s6, 0xe880000
	s_nop 0
	v_add_co_u32_e64 v136, s[6:7], s6, v172
	global_load_dwordx4 v[132:135], v[132:133], off
	s_nop 0
	v_addc_co_u32_e64 v137, s[6:7], 0, v173, s[6:7]
	s_mov_b32 s6, 0xe8c0000
	s_nop 0
	v_add_co_u32_e64 v140, s[6:7], s6, v172
	global_load_dwordx4 v[136:139], v[136:137], off
	s_nop 0
	v_addc_co_u32_e64 v141, s[6:7], 0, v173, s[6:7]
	s_mov_b32 s6, 0xe900000
	s_nop 0
	v_add_co_u32_e64 v144, s[6:7], s6, v172
	global_load_dwordx4 v[140:143], v[140:141], off
	s_nop 0
	v_addc_co_u32_e64 v145, s[6:7], 0, v173, s[6:7]
	s_mov_b32 s6, 0xe940000
	global_load_dwordx4 v[168:171], v[144:145], off
	v_add_co_u32_e64 v144, s[6:7], s6, v172
	s_nop 1
	v_addc_co_u32_e64 v145, s[6:7], 0, v173, s[6:7]
	s_mov_b32 s6, 0xe980000
	global_load_dwordx4 v[192:195], v[144:145], off
	v_add_co_u32_e64 v144, s[6:7], s6, v172
	s_nop 1
	v_addc_co_u32_e64 v145, s[6:7], 0, v173, s[6:7]
	s_mov_b32 s6, 0xe9c0000
	global_load_dwordx4 v[196:199], v[144:145], off
	v_add_co_u32_e64 v144, s[6:7], s6, v172
	s_nop 1
	v_addc_co_u32_e64 v145, s[6:7], 0, v173, s[6:7]
	s_mov_b32 s6, 0xea00000
	global_load_dwordx4 v[218:221], v[144:145], off
	v_add_co_u32_e64 v144, s[6:7], s6, v172
	s_nop 1
	v_addc_co_u32_e64 v145, s[6:7], 0, v173, s[6:7]
	global_load_dwordx4 v[222:225], v[144:145], off
	v_add_u32_e32 v144, 0x8400, v153
	s_waitcnt vmcnt(7)
	ds_write2_b64 v144, v[132:133], v[134:135] offset1:1
	v_add_u32_e32 v132, 0x9480, v153
	s_waitcnt vmcnt(6)
	ds_write2_b64 v132, v[136:137], v[138:139] offset1:1
	v_add_u32_e32 v132, 0xa500, v153
	s_waitcnt vmcnt(5)
	ds_write2_b64 v132, v[140:141], v[142:143] offset1:1
	v_add_u32_e32 v132, 0xb580, v153
	s_waitcnt vmcnt(4)
	ds_write2_b64 v132, v[168:169], v[170:171] offset1:1
	v_add_u32_e32 v132, 0xc600, v153
	s_waitcnt vmcnt(3)
	ds_write2_b64 v132, v[192:193], v[194:195] offset1:1
	v_add_u32_e32 v132, 0xd680, v153
	s_waitcnt vmcnt(2)
	ds_write2_b64 v132, v[196:197], v[198:199] offset1:1
	v_add_u32_e32 v132, 0xe700, v153
	s_waitcnt vmcnt(1)
	ds_write2_b64 v132, v[218:219], v[220:221] offset1:1
	v_add_u32_e32 v132, 0xf780, v153
	s_waitcnt vmcnt(0)
	ds_write2_b64 v132, v[222:223], v[224:225] offset1:1
	s_waitcnt lgkmcnt(0)
	s_barrier
	v_lshlrev_b64 v[132:133], 14, v[166:167]
	v_lshl_add_u64 v[132:133], s[64:65], 0, v[132:133]
	v_lshl_add_u64 v[130:131], v[132:133], 0, v[130:131]
	v_mov_b32_e32 v153, v1
	v_lshl_add_u64 v[134:135], v[130:131], 0, v[152:153]
	s_mov_b32 s6, 0xf640000
	v_add_co_u32_e64 v130, s[6:7], s6, v134
	v_mul_f32 v2, v2, v159
	v_mul_f32 v3, v3, v159
	v_mul_f32 v4, v4, v159
	v_mul_f32 v5, v5, v159
	s_nop 1
	v_addc_co_u32_e64 v131, s[6:7], 0, v135, s[6:7]
	v_mul_f32 v6, v6, v159
	v_mul_f32 v7, v7, v159
	v_mul_f32 v8, v8, v159
	v_mul_f32 v9, v9, v159
	v_mul_f32 v10, v10, v159
	v_mul_f32 v11, v11, v159
	v_mul_f32 v12, v12, v159
	v_mul_f32 v13, v13, v159
	v_mul_f32 v14, v14, v159
	v_mul_f32 v15, v15, v159
	v_mul_f32 v16, v16, v159
	v_mul_f32 v17, v17, v159
	v_mul_f32 v18, v18, v159
	v_mul_f32 v19, v19, v159
	v_mul_f32 v20, v20, v159
	v_mul_f32 v21, v21, v159
	v_mul_f32 v22, v22, v159
	v_mul_f32 v23, v23, v159
	v_mul_f32 v24, v24, v159
	v_mul_f32 v25, v25, v159
	v_mul_f32 v26, v26, v159
	v_mul_f32 v27, v27, v159
	v_mul_f32 v28, v28, v159
	v_mul_f32 v29, v29, v159
	v_mul_f32 v30, v30, v159
	v_mul_f32 v31, v31, v159
	v_mul_f32 v32, v32, v159
	v_mul_f32 v33, v33, v159
	v_mul_f32 v34, v34, v159
	v_mul_f32 v35, v35, v159
	v_mul_f32 v36, v36, v159
	v_mul_f32 v37, v37, v159
	v_mul_f32 v38, v38, v159
	v_mul_f32 v39, v39, v159
	v_mul_f32 v40, v40, v159
	v_mul_f32 v41, v41, v159
	v_mul_f32 v42, v42, v159
	v_mul_f32 v43, v43, v159
	v_mul_f32 v44, v44, v159
	v_mul_f32 v45, v45, v159
	v_mul_f32 v46, v46, v159
	v_mul_f32 v47, v47, v159
	v_mul_f32 v48, v48, v159
	v_mul_f32 v49, v49, v159
	v_mul_f32 v50, v50, v159
	v_mul_f32 v51, v51, v159
	v_mul_f32 v52, v52, v159
	v_mul_f32 v53, v53, v159
	v_mul_f32 v54, v54, v159
	v_mul_f32 v55, v55, v159
	v_mul_f32 v56, v56, v159
	v_mul_f32 v57, v57, v159
	v_mul_f32 v58, v58, v159
	v_mul_f32 v59, v59, v159
	v_mul_f32 v60, v60, v159
	v_mul_f32 v61, v61, v159
	v_mul_f32 v62, v62, v159
	v_mul_f32 v63, v63, v159
	v_mul_f32 v64, v64, v159
	v_mul_f32 v65, v65, v159
	v_mul_f32 v66, v66, v159
	v_mul_f32 v67, v67, v159
	v_mul_f32 v68, v68, v159
	v_mul_f32 v69, v69, v159
	v_mul_f32 v70, v70, v159
	v_mul_f32 v71, v71, v159
	v_mul_f32 v72, v72, v159
	v_mul_f32 v73, v73, v159
	v_mul_f32 v74, v74, v159
	v_mul_f32 v75, v75, v159
	v_mul_f32 v76, v76, v159
	v_mul_f32 v77, v77, v159
	v_mul_f32 v78, v78, v159
	v_mul_f32 v79, v79, v159
	v_mul_f32 v80, v80, v159
	v_mul_f32 v81, v81, v159
	v_mul_f32 v82, v82, v159
	v_mul_f32 v83, v83, v159
	v_mul_f32 v84, v84, v159
	v_mul_f32 v85, v85, v159
	v_mul_f32 v86, v86, v159
	v_mul_f32 v87, v87, v159
	v_mul_f32 v88, v88, v159
	v_mul_f32 v89, v89, v159
	v_mul_f32 v90, v90, v159
	v_mul_f32 v91, v91, v159
	v_mul_f32 v92, v92, v159
	v_mul_f32 v93, v93, v159
	v_mul_f32 v94, v94, v159
	v_mul_f32 v95, v95, v159
	v_mul_f32 v96, v96, v159
	v_mul_f32 v97, v97, v159
	v_mul_f32 v98, v98, v159
	v_mul_f32 v99, v99, v159
	v_mul_f32 v100, v100, v159
	v_mul_f32 v101, v101, v159
	v_mul_f32 v102, v102, v159
	v_mul_f32 v103, v103, v159
	v_mul_f32 v104, v104, v159
	v_mul_f32 v105, v105, v159
	v_mul_f32 v106, v106, v159
	v_mul_f32 v107, v107, v159
	v_mul_f32 v108, v108, v159
	v_mul_f32 v109, v109, v159
	v_mul_f32 v110, v110, v159
	v_mul_f32 v111, v111, v159
	v_mul_f32 v112, v112, v159
	v_mul_f32 v113, v113, v159
	v_mul_f32 v114, v114, v159
	v_mul_f32 v115, v115, v159
	v_mul_f32 v116, v116, v159
	v_mul_f32 v117, v117, v159
	v_mul_f32 v118, v118, v159
	v_mul_f32 v119, v119, v159
	v_mul_f32 v120, v120, v159
	v_mul_f32 v121, v121, v159
	v_mul_f32 v122, v122, v159
	v_mul_f32 v123, v123, v159
	v_mul_f32 v124, v124, v159
	v_mul_f32 v125, v125, v159
	v_mul_f32 v126, v126, v159
	v_mul_f32 v127, v127, v159
	v_mul_f32 v128, v128, v159
	v_mul_f32 v129, v129, v159
	s_mov_b64 s[6:7], 0xf640000
	v_lshl_add_u64 v[142:143], v[134:135], 0, s[6:7]
	v_mov_b32_e32 v130, v234
	v_mov_b32_e32 v131, v235
	v_mov_b32_e32 v132, v236
	v_mov_b32_e32 v133, v237
	v_mov_b32_e32 v134, v238
	v_mov_b32_e32 v135, v239
	v_mov_b32_e32 v136, v240
	v_mov_b32_e32 v137, v241
	v_mov_b32_e32 v138, v242
	v_mov_b32_e32 v139, v243
	v_mov_b32_e32 v140, v244
	v_mov_b32_e32 v141, v245
	v_mov_b32_e32 v166, v246
	v_mov_b32_e32 v167, v247
	v_mov_b32_e32 v168, v248
	v_mov_b32_e32 v169, v249
	global_load_dwordx4 v[234:237], v[142:143], off offset:128
	global_load_dwordx4 v[238:241], v[142:143], off offset:160
	global_load_dwordx4 v[242:245], v[142:143], off offset:192
	global_load_dwordx4 v[246:249], v[142:143], off offset:224
	v_fma_f32 v144, 0, v191, v190
	v_add_f32_e32 v145, v190, v191
	v_exp_f32_e32 v144, v144
	v_exp_f32_e32 v145, v145
	v_fmamk_f32 v153, v191, 0x42480000, v190
	s_waitcnt vmcnt(4)
	v_lshlrev_b32_e32 v170, 16, v130
	v_and_b32_e32 v171, 0xffff0000, v130
	v_fma_f32 v130, 2.0, v191, v190
	v_pk_mul_f32 v[144:145], v[144:145], v[170:171]
	v_exp_f32_e32 v170, v130
	v_fmamk_f32 v130, v191, 0x40400000, v190
	v_exp_f32_e32 v171, v130
	v_cvt_pk_bf16_f32 v130, v144, v145
	v_lshlrev_b32_e32 v144, 16, v131
	v_and_b32_e32 v145, 0xffff0000, v131
	v_fma_f32 v131, 4.0, v191, v190
	v_pk_mul_f32 v[144:145], v[170:171], v[144:145]
	v_exp_f32_e32 v170, v131
	v_fmamk_f32 v131, v191, 0x40a00000, v190
	v_exp_f32_e32 v171, v131
	v_cvt_pk_bf16_f32 v131, v144, v145
	v_lshlrev_b32_e32 v144, 16, v132
	v_and_b32_e32 v145, 0xffff0000, v132
	v_fmamk_f32 v132, v191, 0x40c00000, v190
	v_pk_mul_f32 v[144:145], v[170:171], v[144:145]
	v_exp_f32_e32 v170, v132
	v_fmamk_f32 v132, v191, 0x40e00000, v190
	v_exp_f32_e32 v171, v132
	v_cvt_pk_bf16_f32 v132, v144, v145
	v_lshlrev_b32_e32 v144, 16, v133
	v_and_b32_e32 v145, 0xffff0000, v133
	v_fmamk_f32 v133, v191, 0x41800000, v190
	v_pk_mul_f32 v[144:145], v[170:171], v[144:145]
	v_exp_f32_e32 v170, v133
	v_fmamk_f32 v133, v191, 0x41880000, v190
	v_exp_f32_e32 v171, v133
	v_cvt_pk_bf16_f32 v133, v144, v145
	s_waitcnt vmcnt(4)
	v_lshlrev_b32_e32 v144, 16, v134
	v_and_b32_e32 v145, 0xffff0000, v134
	v_fmamk_f32 v134, v191, 0x41900000, v190
	v_pk_mul_f32 v[144:145], v[170:171], v[144:145]
	v_exp_f32_e32 v170, v134
	v_fmamk_f32 v134, v191, 0x41980000, v190
	v_exp_f32_e32 v171, v134
	v_cvt_pk_bf16_f32 v134, v144, v145
	v_lshlrev_b32_e32 v144, 16, v135
	v_and_b32_e32 v145, 0xffff0000, v135
	v_fmamk_f32 v135, v191, 0x41a00000, v190
	v_pk_mul_f32 v[144:145], v[170:171], v[144:145]
	v_exp_f32_e32 v170, v135
	v_fmamk_f32 v135, v191, 0x41a80000, v190
	v_exp_f32_e32 v171, v135
	v_cvt_pk_bf16_f32 v135, v144, v145
	v_lshlrev_b32_e32 v144, 16, v136
	v_and_b32_e32 v145, 0xffff0000, v136
	v_fmamk_f32 v136, v191, 0x41b00000, v190
	v_pk_mul_f32 v[144:145], v[170:171], v[144:145]
	v_exp_f32_e32 v170, v136
	v_fmamk_f32 v136, v191, 0x41b80000, v190
	v_exp_f32_e32 v171, v136
	v_cvt_pk_bf16_f32 v136, v144, v145
	v_lshlrev_b32_e32 v144, 16, v137
	v_and_b32_e32 v145, 0xffff0000, v137
	v_fmamk_f32 v137, v191, 0x42000000, v190
	v_pk_mul_f32 v[144:145], v[170:171], v[144:145]
	v_exp_f32_e32 v170, v137
	v_fmamk_f32 v137, v191, 0x42040000, v190
	v_exp_f32_e32 v171, v137
	v_cvt_pk_bf16_f32 v137, v144, v145
	s_waitcnt vmcnt(4)
	v_lshlrev_b32_e32 v144, 16, v138
	v_and_b32_e32 v145, 0xffff0000, v138
	v_fmamk_f32 v138, v191, 0x42080000, v190
	v_pk_mul_f32 v[144:145], v[170:171], v[144:145]
	v_exp_f32_e32 v170, v138
	v_fmamk_f32 v138, v191, 0x420c0000, v190
	v_exp_f32_e32 v171, v138
	v_cvt_pk_bf16_f32 v138, v144, v145
	v_lshlrev_b32_e32 v144, 16, v139
	v_and_b32_e32 v145, 0xffff0000, v139
	v_fmamk_f32 v139, v191, 0x42100000, v190
	v_pk_mul_f32 v[144:145], v[170:171], v[144:145]
	v_exp_f32_e32 v170, v139
	v_fmamk_f32 v139, v191, 0x42140000, v190
	v_exp_f32_e32 v171, v139
	v_cvt_pk_bf16_f32 v139, v144, v145
	v_lshlrev_b32_e32 v144, 16, v140
	v_and_b32_e32 v145, 0xffff0000, v140
	v_fmamk_f32 v140, v191, 0x42180000, v190
	v_pk_mul_f32 v[144:145], v[170:171], v[144:145]
	v_exp_f32_e32 v170, v140
	v_fmamk_f32 v140, v191, 0x421c0000, v190
	v_exp_f32_e32 v171, v140
	v_cvt_pk_bf16_f32 v140, v144, v145
	v_lshlrev_b32_e32 v144, 16, v141
	v_and_b32_e32 v145, 0xffff0000, v141
	v_fmamk_f32 v141, v191, 0x42400000, v190
	v_pk_mul_f32 v[144:145], v[170:171], v[144:145]
	v_exp_f32_e32 v170, v141
	v_fmamk_f32 v141, v191, 0x42440000, v190
	v_exp_f32_e32 v171, v141
	v_cvt_pk_bf16_f32 v141, v144, v145
	s_waitcnt vmcnt(4)
	v_lshlrev_b32_e32 v144, 16, v166
	v_and_b32_e32 v145, 0xffff0000, v166
	v_pk_mul_f32 v[144:145], v[170:171], v[144:145]
	v_exp_f32_e32 v170, v153
	v_fmamk_f32 v153, v191, 0x424c0000, v190
	v_exp_f32_e32 v171, v153
	v_cvt_pk_bf16_f32 v166, v144, v145
	v_lshlrev_b32_e32 v144, 16, v167
	v_and_b32_e32 v145, 0xffff0000, v167
	v_fmamk_f32 v153, v191, 0x42500000, v190
	v_pk_mul_f32 v[144:145], v[170:171], v[144:145]
	v_exp_f32_e32 v170, v153
	v_fmamk_f32 v153, v191, 0x42540000, v190
	v_exp_f32_e32 v171, v153
	v_cvt_pk_bf16_f32 v167, v144, v145
	v_lshlrev_b32_e32 v144, 16, v168
	v_and_b32_e32 v145, 0xffff0000, v168
	v_fmamk_f32 v153, v191, 0x42580000, v190
	v_pk_mul_f32 v[144:145], v[170:171], v[144:145]
	v_exp_f32_e32 v170, v153
	v_fmamk_f32 v153, v191, 0x425c0000, v190
	v_exp_f32_e32 v171, v153
	v_cvt_pk_bf16_f32 v168, v144, v145
	v_lshlrev_b32_e32 v144, 16, v169
	v_and_b32_e32 v145, 0xffff0000, v169
	v_pk_mul_f32 v[144:145], v[170:171], v[144:145]
	s_nop 0
	v_cvt_pk_bf16_f32 v169, v144, v145
	ds_read2_b64 v[170:173], v179 offset1:1
	ds_read2_b64 v[192:195], v179 offset0:4 offset1:5
	ds_read2_b64 v[196:199], v179 offset0:8 offset1:9
	ds_read2_b64 v[218:221], v179 offset0:12 offset1:13
	s_waitcnt lgkmcnt(3)
	v_mfma_f32_32x32x16_bf16 v[2:17], v[170:173], v[130:133], v[2:17]
	v_add_u32_e32 v144, 0x2100, v179
	ds_read2_b64 v[170:173], v144 offset1:1
	s_waitcnt lgkmcnt(3)
	v_mfma_f32_32x32x16_bf16 v[2:17], v[192:195], v[134:137], v[2:17]
	v_add_u32_e32 v144, 0x2120, v179
	ds_read2_b64 v[192:195], v144 offset1:1
	s_waitcnt lgkmcnt(3)
	v_mfma_f32_32x32x16_bf16 v[2:17], v[196:199], v[138:141], v[2:17]
	v_add_u32_e32 v144, 0x2140, v179
	ds_read2_b64 v[196:199], v144 offset1:1
	s_waitcnt lgkmcnt(3)
	v_mfma_f32_32x32x16_bf16 v[2:17], v[218:221], v[166:169], v[2:17]
	v_add_u32_e32 v144, 0x2160, v179
	ds_read2_b64 v[218:221], v144 offset1:1
	s_waitcnt lgkmcnt(3)
	v_mfma_f32_32x32x16_bf16 v[18:33], v[170:173], v[130:133], v[18:33]
	v_add_u32_e32 v144, 0x4200, v179
	ds_read2_b64 v[170:173], v144 offset1:1
	s_waitcnt lgkmcnt(3)
	v_mfma_f32_32x32x16_bf16 v[18:33], v[192:195], v[134:137], v[18:33]
	v_add_u32_e32 v144, 0x4220, v179
	ds_read2_b64 v[192:195], v144 offset1:1
	s_waitcnt lgkmcnt(3)
	v_mfma_f32_32x32x16_bf16 v[18:33], v[196:199], v[138:141], v[18:33]
	v_add_u32_e32 v144, 0x4240, v179
	ds_read2_b64 v[196:199], v144 offset1:1
	s_waitcnt lgkmcnt(3)
	v_mfma_f32_32x32x16_bf16 v[18:33], v[218:221], v[166:169], v[18:33]
	v_add_u32_e32 v144, 0x4260, v179
	ds_read2_b64 v[218:221], v144 offset1:1
	s_waitcnt lgkmcnt(3)
	v_mfma_f32_32x32x16_bf16 v[34:49], v[170:173], v[130:133], v[34:49]
	v_add_u32_e32 v144, 0x6300, v179
	ds_read2_b64 v[170:173], v144 offset1:1
	s_waitcnt lgkmcnt(3)
	v_mfma_f32_32x32x16_bf16 v[34:49], v[192:195], v[134:137], v[34:49]
	v_add_u32_e32 v144, 0x6320, v179
	ds_read2_b64 v[192:195], v144 offset1:1
	s_waitcnt lgkmcnt(3)
	v_mfma_f32_32x32x16_bf16 v[34:49], v[196:199], v[138:141], v[34:49]
	v_add_u32_e32 v144, 0x6340, v179
	ds_read2_b64 v[196:199], v144 offset1:1
	s_waitcnt lgkmcnt(3)
	v_mfma_f32_32x32x16_bf16 v[34:49], v[218:221], v[166:169], v[34:49]
	v_add_u32_e32 v144, 0x6360, v179
	ds_read2_b64 v[218:221], v144 offset1:1
	s_waitcnt lgkmcnt(3)
	v_mfma_f32_32x32x16_bf16 v[50:65], v[170:173], v[130:133], v[50:65]
	v_add_u32_e32 v144, 0x8400, v179
	ds_read2_b64 v[170:173], v144 offset1:1
	s_waitcnt lgkmcnt(3)
	v_mfma_f32_32x32x16_bf16 v[50:65], v[192:195], v[134:137], v[50:65]
	v_add_u32_e32 v144, 0x8420, v179
	ds_read2_b64 v[192:195], v144 offset1:1
	s_waitcnt lgkmcnt(3)
	v_mfma_f32_32x32x16_bf16 v[50:65], v[196:199], v[138:141], v[50:65]
	v_add_u32_e32 v144, 0x8440, v179
	ds_read2_b64 v[196:199], v144 offset1:1
	s_waitcnt lgkmcnt(3)
	v_mfma_f32_32x32x16_bf16 v[50:65], v[218:221], v[166:169], v[50:65]
	v_add_u32_e32 v144, 0x8460, v179
	ds_read2_b64 v[218:221], v144 offset1:1
	s_waitcnt lgkmcnt(3)
	v_mfma_f32_32x32x16_bf16 v[66:81], v[170:173], v[130:133], v[66:81]
	v_add_u32_e32 v144, 0xa500, v179
	ds_read2_b64 v[170:173], v144 offset1:1
	s_waitcnt lgkmcnt(3)
	v_mfma_f32_32x32x16_bf16 v[66:81], v[192:195], v[134:137], v[66:81]
	v_add_u32_e32 v144, 0xa520, v179
	ds_read2_b64 v[192:195], v144 offset1:1
	s_waitcnt lgkmcnt(3)
	v_mfma_f32_32x32x16_bf16 v[66:81], v[196:199], v[138:141], v[66:81]
	v_add_u32_e32 v144, 0xa540, v179
	ds_read2_b64 v[196:199], v144 offset1:1
	s_waitcnt lgkmcnt(3)
	v_mfma_f32_32x32x16_bf16 v[66:81], v[218:221], v[166:169], v[66:81]
	v_add_u32_e32 v144, 0xa560, v179
	ds_read2_b64 v[218:221], v144 offset1:1
	s_waitcnt lgkmcnt(3)
	v_mfma_f32_32x32x16_bf16 v[82:97], v[170:173], v[130:133], v[82:97]
	v_add_u32_e32 v144, 0xc600, v179
	ds_read2_b64 v[170:173], v144 offset1:1
	s_waitcnt lgkmcnt(3)
	v_mfma_f32_32x32x16_bf16 v[82:97], v[192:195], v[134:137], v[82:97]
	v_add_u32_e32 v144, 0xc620, v179
	ds_read2_b64 v[192:195], v144 offset1:1
	s_waitcnt lgkmcnt(3)
	v_mfma_f32_32x32x16_bf16 v[82:97], v[196:199], v[138:141], v[82:97]
	v_add_u32_e32 v144, 0xc640, v179
	ds_read2_b64 v[196:199], v144 offset1:1
	s_waitcnt lgkmcnt(3)
	v_mfma_f32_32x32x16_bf16 v[82:97], v[218:221], v[166:169], v[82:97]
	v_add_u32_e32 v144, 0xc660, v179
	ds_read2_b64 v[218:221], v144 offset1:1
	s_waitcnt lgkmcnt(3)
	v_mfma_f32_32x32x16_bf16 v[98:113], v[170:173], v[130:133], v[98:113]
	v_add_u32_e32 v144, 0xe700, v179
	ds_read2_b64 v[170:173], v144 offset1:1
	s_waitcnt lgkmcnt(3)
	v_mfma_f32_32x32x16_bf16 v[98:113], v[192:195], v[134:137], v[98:113]
	v_add_u32_e32 v144, 0xe720, v179
	ds_read2_b64 v[192:195], v144 offset1:1
	s_waitcnt lgkmcnt(3)
	v_mfma_f32_32x32x16_bf16 v[98:113], v[196:199], v[138:141], v[98:113]
	v_add_u32_e32 v144, 0xe740, v179
	ds_read2_b64 v[196:199], v144 offset1:1
	s_waitcnt lgkmcnt(3)
	v_mfma_f32_32x32x16_bf16 v[98:113], v[218:221], v[166:169], v[98:113]
	v_add_u32_e32 v144, 0xe760, v179
	ds_read2_b64 v[218:221], v144 offset1:1
	s_waitcnt lgkmcnt(3)
	v_mfma_f32_32x32x16_bf16 v[114:129], v[170:173], v[130:133], v[114:129]
	s_waitcnt lgkmcnt(2)
	v_mfma_f32_32x32x16_bf16 v[114:129], v[192:195], v[134:137], v[114:129]
	s_waitcnt lgkmcnt(1)
	v_mfma_f32_32x32x16_bf16 v[114:129], v[196:199], v[138:141], v[114:129]
	s_waitcnt lgkmcnt(0)
	v_mfma_f32_32x32x16_bf16 v[114:129], v[218:221], v[166:169], v[114:129]
	v_fmamk_f32 v134, v191, 0x42800000, v190
	v_fmamk_f32 v135, v191, 0x42820000, v190
	v_exp_f32_e32 v134, v134
	v_exp_f32_e32 v135, v135
	v_fmamk_f32 v138, v191, 0x42a00000, v190
	v_fmamk_f32 v139, v191, 0x42a20000, v190
	v_exp_f32_e32 v138, v138
	v_exp_f32_e32 v139, v139
	v_fmamk_f32 v144, v191, 0x42c00000, v190
	v_fmamk_f32 v145, v191, 0x42c20000, v190
	v_exp_f32_e32 v144, v144
	v_exp_f32_e32 v145, v145
	v_fmamk_f32 v153, v191, 0x42e00000, v190
	s_waitcnt vmcnt(0)
	v_mov_b32_e32 v130, v234
	v_mov_b32_e32 v131, v235
	v_mov_b32_e32 v132, v236
	v_mov_b32_e32 v133, v237
	v_lshlrev_b32_e32 v136, 16, v130
	v_and_b32_e32 v137, 0xffff0000, v130
	v_pk_mul_f32 v[134:135], v[134:135], v[136:137]
	v_lshlrev_b32_e32 v136, 16, v131
	v_cvt_pk_bf16_f32 v130, v134, v135
	v_fmamk_f32 v134, v191, 0x42840000, v190
	v_fmamk_f32 v135, v191, 0x42860000, v190
	v_exp_f32_e32 v134, v134
	v_exp_f32_e32 v135, v135
	v_and_b32_e32 v137, 0xffff0000, v131
	v_pk_mul_f32 v[134:135], v[134:135], v[136:137]
	s_nop 0
	v_cvt_pk_bf16_f32 v131, v134, v135
	v_fmamk_f32 v134, v191, 0x42880000, v190
	v_fmamk_f32 v135, v191, 0x428a0000, v190
	v_exp_f32_e32 v134, v134
	v_exp_f32_e32 v135, v135
	v_lshlrev_b32_e32 v136, 16, v132
	v_and_b32_e32 v137, 0xffff0000, v132
	v_pk_mul_f32 v[134:135], v[134:135], v[136:137]
	s_nop 0
	v_cvt_pk_bf16_f32 v132, v134, v135
	v_fmamk_f32 v134, v191, 0x428c0000, v190
	v_fmamk_f32 v135, v191, 0x428e0000, v190
	v_exp_f32_e32 v134, v134
	v_exp_f32_e32 v135, v135
	v_lshlrev_b32_e32 v136, 16, v133
	v_and_b32_e32 v137, 0xffff0000, v133
	v_pk_mul_f32 v[134:135], v[134:135], v[136:137]
	s_nop 0
	v_cvt_pk_bf16_f32 v133, v134, v135
	s_waitcnt vmcnt(0)
	v_mov_b32_e32 v134, v238
	v_mov_b32_e32 v135, v239
	v_mov_b32_e32 v136, v240
	v_mov_b32_e32 v137, v241
	v_lshlrev_b32_e32 v140, 16, v134
	v_and_b32_e32 v141, 0xffff0000, v134
	v_pk_mul_f32 v[138:139], v[138:139], v[140:141]
	v_lshlrev_b32_e32 v140, 16, v135
	v_cvt_pk_bf16_f32 v134, v138, v139
	v_fmamk_f32 v138, v191, 0x42a40000, v190
	v_fmamk_f32 v139, v191, 0x42a60000, v190
	v_exp_f32_e32 v138, v138
	v_exp_f32_e32 v139, v139
	v_and_b32_e32 v141, 0xffff0000, v135
	v_pk_mul_f32 v[138:139], v[138:139], v[140:141]
	s_nop 0
	v_cvt_pk_bf16_f32 v135, v138, v139
	v_fmamk_f32 v138, v191, 0x42a80000, v190
	v_fmamk_f32 v139, v191, 0x42aa0000, v190
	v_exp_f32_e32 v138, v138
	v_exp_f32_e32 v139, v139
	v_lshlrev_b32_e32 v140, 16, v136
	v_and_b32_e32 v141, 0xffff0000, v136
	v_pk_mul_f32 v[138:139], v[138:139], v[140:141]
	s_nop 0
	v_cvt_pk_bf16_f32 v136, v138, v139
	v_fmamk_f32 v138, v191, 0x42ac0000, v190
	v_fmamk_f32 v139, v191, 0x42ae0000, v190
	v_exp_f32_e32 v138, v138
	v_exp_f32_e32 v139, v139
	v_lshlrev_b32_e32 v140, 16, v137
	v_and_b32_e32 v141, 0xffff0000, v137
	v_pk_mul_f32 v[138:139], v[138:139], v[140:141]
	s_nop 0
	v_cvt_pk_bf16_f32 v137, v138, v139
	s_waitcnt vmcnt(0)
	v_mov_b32_e32 v138, v242
	v_mov_b32_e32 v139, v243
	v_mov_b32_e32 v140, v244
	v_mov_b32_e32 v141, v245
	v_lshlrev_b32_e32 v166, 16, v138
	v_and_b32_e32 v167, 0xffff0000, v138
	v_pk_mul_f32 v[144:145], v[144:145], v[166:167]
	v_lshlrev_b32_e32 v166, 16, v139
	v_cvt_pk_bf16_f32 v138, v144, v145
	v_fmamk_f32 v144, v191, 0x42c40000, v190
	v_fmamk_f32 v145, v191, 0x42c60000, v190
	v_exp_f32_e32 v144, v144
	v_exp_f32_e32 v145, v145
	v_and_b32_e32 v167, 0xffff0000, v139
	v_pk_mul_f32 v[144:145], v[144:145], v[166:167]
	s_nop 0
	v_cvt_pk_bf16_f32 v139, v144, v145
	v_fmamk_f32 v144, v191, 0x42c80000, v190
	v_fmamk_f32 v145, v191, 0x42ca0000, v190
	v_exp_f32_e32 v144, v144
	v_exp_f32_e32 v145, v145
	v_lshlrev_b32_e32 v166, 16, v140
	v_and_b32_e32 v167, 0xffff0000, v140
	v_pk_mul_f32 v[144:145], v[144:145], v[166:167]
	s_nop 0
	v_cvt_pk_bf16_f32 v140, v144, v145
	v_fmamk_f32 v144, v191, 0x42cc0000, v190
	v_fmamk_f32 v145, v191, 0x42ce0000, v190
	v_exp_f32_e32 v144, v144
	v_exp_f32_e32 v145, v145
	v_lshlrev_b32_e32 v166, 16, v141
	v_and_b32_e32 v167, 0xffff0000, v141
	v_pk_mul_f32 v[144:145], v[144:145], v[166:167]
	s_nop 0
	v_cvt_pk_bf16_f32 v141, v144, v145
	v_exp_f32_e32 v166, v153
	v_fmamk_f32 v153, v191, 0x42e20000, v190
	v_exp_f32_e32 v167, v153
	v_fmamk_f32 v153, v191, 0x42e40000, v190
	s_waitcnt vmcnt(0)
	v_mov_b32_e32 v142, v246
	v_mov_b32_e32 v143, v247
	v_mov_b32_e32 v144, v248
	v_mov_b32_e32 v145, v249
	v_lshlrev_b32_e32 v168, 16, v142
	v_and_b32_e32 v169, 0xffff0000, v142
	v_pk_mul_f32 v[166:167], v[166:167], v[168:169]
	v_lshlrev_b32_e32 v168, 16, v143
	v_cvt_pk_bf16_f32 v142, v166, v167
	v_exp_f32_e32 v166, v153
	v_fmamk_f32 v153, v191, 0x42e60000, v190
	v_exp_f32_e32 v167, v153
	v_and_b32_e32 v169, 0xffff0000, v143
	v_fmamk_f32 v153, v191, 0x42e80000, v190
	v_pk_mul_f32 v[166:167], v[166:167], v[168:169]
	s_nop 0
	v_cvt_pk_bf16_f32 v143, v166, v167
	v_exp_f32_e32 v166, v153
	v_fmamk_f32 v153, v191, 0x42ea0000, v190
	v_exp_f32_e32 v167, v153
	v_lshlrev_b32_e32 v168, 16, v144
	v_and_b32_e32 v169, 0xffff0000, v144
	v_fmamk_f32 v153, v191, 0x42ec0000, v190
	v_pk_mul_f32 v[166:167], v[166:167], v[168:169]
	v_fmac_f32_e32 v190, 0x42ee0000, v191
	v_cvt_pk_bf16_f32 v144, v166, v167
	v_exp_f32_e32 v166, v153
	v_exp_f32_e32 v167, v190
	v_lshlrev_b32_e32 v168, 16, v145
	v_and_b32_e32 v169, 0xffff0000, v145
	v_pk_mul_f32 v[166:167], v[166:167], v[168:169]
	s_nop 0
	v_cvt_pk_bf16_f32 v145, v166, v167
	ds_read2_b64 v[166:169], v179 offset0:16 offset1:17
	ds_read2_b64 v[170:173], v179 offset0:20 offset1:21
	ds_read2_b64 v[190:193], v179 offset0:24 offset1:25
	ds_read2_b64 v[194:197], v179 offset0:28 offset1:29
	s_waitcnt lgkmcnt(3)
	v_mfma_f32_32x32x16_bf16 v[2:17], v[166:169], v[130:133], v[2:17]
	v_add_u32_e32 v153, 0x2180, v179
	ds_read2_b64 v[166:169], v153 offset1:1
	s_waitcnt lgkmcnt(3)
	v_mfma_f32_32x32x16_bf16 v[2:17], v[170:173], v[134:137], v[2:17]
	v_add_u32_e32 v153, 0x21a0, v179
	ds_read2_b64 v[170:173], v153 offset1:1
	s_waitcnt lgkmcnt(3)
	v_mfma_f32_32x32x16_bf16 v[2:17], v[190:193], v[138:141], v[2:17]
	v_add_u32_e32 v153, 0x21c0, v179
	ds_read2_b64 v[190:193], v153 offset1:1
	s_waitcnt lgkmcnt(3)
	v_mfma_f32_32x32x16_bf16 v[2:17], v[194:197], v[142:145], v[2:17]
	v_add_u32_e32 v153, 0x21e0, v179
	ds_read2_b64 v[194:197], v153 offset1:1
	s_waitcnt lgkmcnt(3)
	v_mfma_f32_32x32x16_bf16 v[18:33], v[166:169], v[130:133], v[18:33]
	v_add_u32_e32 v153, 0x4280, v179
	ds_read2_b64 v[166:169], v153 offset1:1
	s_waitcnt lgkmcnt(3)
	v_mfma_f32_32x32x16_bf16 v[18:33], v[170:173], v[134:137], v[18:33]
	v_add_u32_e32 v153, 0x42a0, v179
	ds_read2_b64 v[170:173], v153 offset1:1
	s_waitcnt lgkmcnt(3)
	v_mfma_f32_32x32x16_bf16 v[18:33], v[190:193], v[138:141], v[18:33]
	v_add_u32_e32 v153, 0x42c0, v179
	ds_read2_b64 v[190:193], v153 offset1:1
	s_waitcnt lgkmcnt(3)
	v_mfma_f32_32x32x16_bf16 v[18:33], v[194:197], v[142:145], v[18:33]
	v_add_u32_e32 v153, 0x42e0, v179
	ds_read2_b64 v[194:197], v153 offset1:1
	s_waitcnt lgkmcnt(3)
	v_mfma_f32_32x32x16_bf16 v[34:49], v[166:169], v[130:133], v[34:49]
	v_add_u32_e32 v153, 0x6380, v179
	ds_read2_b64 v[166:169], v153 offset1:1
	s_waitcnt lgkmcnt(3)
	v_mfma_f32_32x32x16_bf16 v[34:49], v[170:173], v[134:137], v[34:49]
	v_add_u32_e32 v153, 0x63a0, v179
	ds_read2_b64 v[170:173], v153 offset1:1
	s_waitcnt lgkmcnt(3)
	v_mfma_f32_32x32x16_bf16 v[34:49], v[190:193], v[138:141], v[34:49]
	v_add_u32_e32 v153, 0x63c0, v179
	ds_read2_b64 v[190:193], v153 offset1:1
	s_waitcnt lgkmcnt(3)
	v_mfma_f32_32x32x16_bf16 v[34:49], v[194:197], v[142:145], v[34:49]
	v_add_u32_e32 v153, 0x63e0, v179
	ds_read2_b64 v[194:197], v153 offset1:1
	s_waitcnt lgkmcnt(3)
	v_mfma_f32_32x32x16_bf16 v[50:65], v[166:169], v[130:133], v[50:65]
	v_add_u32_e32 v153, 0x8480, v179
	ds_read2_b64 v[166:169], v153 offset1:1
	s_waitcnt lgkmcnt(3)
	v_mfma_f32_32x32x16_bf16 v[50:65], v[170:173], v[134:137], v[50:65]
	v_add_u32_e32 v153, 0x84a0, v179
	ds_read2_b64 v[170:173], v153 offset1:1
	s_waitcnt lgkmcnt(3)
	v_mfma_f32_32x32x16_bf16 v[50:65], v[190:193], v[138:141], v[50:65]
	v_add_u32_e32 v153, 0x84c0, v179
	ds_read2_b64 v[190:193], v153 offset1:1
	s_waitcnt lgkmcnt(3)
	v_mfma_f32_32x32x16_bf16 v[50:65], v[194:197], v[142:145], v[50:65]
	v_add_u32_e32 v153, 0x84e0, v179
	ds_read2_b64 v[194:197], v153 offset1:1
	s_waitcnt lgkmcnt(3)
	v_mfma_f32_32x32x16_bf16 v[66:81], v[166:169], v[130:133], v[66:81]
	v_add_u32_e32 v153, 0xa580, v179
	ds_read2_b64 v[166:169], v153 offset1:1
	s_waitcnt lgkmcnt(3)
	v_mfma_f32_32x32x16_bf16 v[66:81], v[170:173], v[134:137], v[66:81]
	v_add_u32_e32 v153, 0xa5a0, v179
	ds_read2_b64 v[170:173], v153 offset1:1
	s_waitcnt lgkmcnt(3)
	v_mfma_f32_32x32x16_bf16 v[66:81], v[190:193], v[138:141], v[66:81]
	v_add_u32_e32 v153, 0xa5c0, v179
	ds_read2_b64 v[190:193], v153 offset1:1
	s_waitcnt lgkmcnt(3)
	v_mfma_f32_32x32x16_bf16 v[66:81], v[194:197], v[142:145], v[66:81]
	v_add_u32_e32 v153, 0xa5e0, v179
	ds_read2_b64 v[194:197], v153 offset1:1
	s_waitcnt lgkmcnt(3)
	v_mfma_f32_32x32x16_bf16 v[82:97], v[166:169], v[130:133], v[82:97]
	v_add_u32_e32 v153, 0xc680, v179
	ds_read2_b64 v[166:169], v153 offset1:1
	s_waitcnt lgkmcnt(3)
	v_mfma_f32_32x32x16_bf16 v[82:97], v[170:173], v[134:137], v[82:97]
	v_add_u32_e32 v153, 0xc6a0, v179
	ds_read2_b64 v[170:173], v153 offset1:1
	s_waitcnt lgkmcnt(3)
	v_mfma_f32_32x32x16_bf16 v[82:97], v[190:193], v[138:141], v[82:97]
	v_add_u32_e32 v153, 0xc6c0, v179
	ds_read2_b64 v[190:193], v153 offset1:1
	s_waitcnt lgkmcnt(3)
	v_mfma_f32_32x32x16_bf16 v[82:97], v[194:197], v[142:145], v[82:97]
	v_add_u32_e32 v153, 0xc6e0, v179
	ds_read2_b64 v[194:197], v153 offset1:1
	s_waitcnt lgkmcnt(3)
	v_mfma_f32_32x32x16_bf16 v[98:113], v[166:169], v[130:133], v[98:113]
	v_add_u32_e32 v153, 0xe780, v179
	ds_read2_b64 v[166:169], v153 offset1:1
	s_waitcnt lgkmcnt(3)
	v_mfma_f32_32x32x16_bf16 v[98:113], v[170:173], v[134:137], v[98:113]
	v_add_u32_e32 v153, 0xe7a0, v179
	ds_read2_b64 v[170:173], v153 offset1:1
	s_waitcnt lgkmcnt(3)
	v_mfma_f32_32x32x16_bf16 v[98:113], v[190:193], v[138:141], v[98:113]
	v_add_u32_e32 v153, 0xe7c0, v179
	ds_read2_b64 v[190:193], v153 offset1:1
	s_waitcnt lgkmcnt(3)
	v_mfma_f32_32x32x16_bf16 v[98:113], v[194:197], v[142:145], v[98:113]
	v_add_u32_e32 v153, 0xe7e0, v179
	ds_read2_b64 v[194:197], v153 offset1:1
	s_waitcnt lgkmcnt(3)
	v_mfma_f32_32x32x16_bf16 v[114:129], v[166:169], v[130:133], v[114:129]
	s_waitcnt lgkmcnt(2)
	v_mfma_f32_32x32x16_bf16 v[114:129], v[170:173], v[134:137], v[114:129]
	s_waitcnt lgkmcnt(1)
	v_mfma_f32_32x32x16_bf16 v[114:129], v[190:193], v[138:141], v[114:129]
	s_waitcnt lgkmcnt(0)
	v_mfma_f32_32x32x16_bf16 v[114:129], v[194:197], v[142:145], v[114:129]
	s_add_i32 s66, s66, 1
	s_add_i32 s67, s67, -1
	s_cmp_eq_u32 s67, -1
	s_cbranch_scc0 .LBB0_327
	s_and_b64 vcc, exec, s[4:5]
	s_mov_b64 s[4:5], -1
	s_cbranch_vccnz .LBB0_330
	s_mov_b64 s[4:5], 0
